# PEER phase: V-pass epilogue loads hoisted (one round trip instead of eight) on top of sorted/pipelined/MFMA version
# speedup vs baseline: 1.0108x; 1.0108x over previous
.Lp10v_loop:
	s_waitcnt vmcnt(15) lgkmcnt(3)
	v_cvt_scalef32_pk_f32_fp4 v[8:9], v44, 1.0
	v_cvt_scalef32_pk_f32_fp4 v[10:11], v44, 1.0 op_sel:[1,0,0]
	v_cvt_scalef32_pk_f32_fp4 v[12:13], v44, 1.0 op_sel:[0,1,0]
	v_cvt_scalef32_pk_f32_fp4 v[14:15], v44, 1.0 op_sel:[1,1,0]
	v_cvt_scalef32_pk_f32_fp4 v[16:17], v45, 1.0
	v_cvt_scalef32_pk_f32_fp4 v[18:19], v45, 1.0 op_sel:[1,0,0]
	v_cvt_scalef32_pk_f32_fp4 v[64:65], v45, 1.0 op_sel:[0,1,0]
	v_cvt_scalef32_pk_f32_fp4 v[66:67], v45, 1.0 op_sel:[1,1,0]
	v_pk_fma_f32 v[24:25], v[8:9], v[188:189], v[24:25] op_sel_hi:[1,0,1]
	v_pk_fma_f32 v[26:27], v[10:11], v[188:189], v[26:27] op_sel_hi:[1,0,1]
	v_pk_fma_f32 v[40:41], v[12:13], v[188:189], v[40:41] op_sel_hi:[1,0,1]
	v_pk_fma_f32 v[42:43], v[14:15], v[188:189], v[42:43] op_sel_hi:[1,0,1]
	v_cvt_scalef32_pk_f32_fp4 v[68:69], v46, 1.0
	v_cvt_scalef32_pk_f32_fp4 v[70:71], v46, 1.0 op_sel:[1,0,0]
	v_cvt_scalef32_pk_f32_fp4 v[72:73], v46, 1.0 op_sel:[0,1,0]
	v_cvt_scalef32_pk_f32_fp4 v[74:75], v46, 1.0 op_sel:[1,1,0]
	v_pk_fma_f32 v[36:37], v[16:17], v[188:189], v[36:37] op_sel_hi:[1,0,1]
	v_pk_fma_f32 v[38:39], v[18:19], v[188:189], v[38:39] op_sel_hi:[1,0,1]
	v_pk_fma_f32 v[4:5], v[64:65], v[188:189], v[4:5] op_sel_hi:[1,0,1]
	v_pk_fma_f32 v[6:7], v[66:67], v[188:189], v[6:7] op_sel_hi:[1,0,1]
	v_cvt_scalef32_pk_f32_fp4 v[8:9], v47, 1.0
	v_cvt_scalef32_pk_f32_fp4 v[10:11], v47, 1.0 op_sel:[1,0,0]
	v_cvt_scalef32_pk_f32_fp4 v[12:13], v47, 1.0 op_sel:[0,1,0]
	v_cvt_scalef32_pk_f32_fp4 v[14:15], v47, 1.0 op_sel:[1,1,0]
	v_pk_fma_f32 v[32:33], v[68:69], v[188:189], v[32:33] op_sel_hi:[1,0,1]
	v_pk_fma_f32 v[34:35], v[70:71], v[188:189], v[34:35] op_sel_hi:[1,0,1]
	v_pk_fma_f32 v[28:29], v[72:73], v[188:189], v[28:29] op_sel_hi:[1,0,1]
	v_pk_fma_f32 v[30:31], v[74:75], v[188:189], v[30:31] op_sel_hi:[1,0,1]
	v_pk_fma_f32 v[20:21], v[8:9], v[188:189], v[20:21] op_sel_hi:[1,0,1]
	v_pk_fma_f32 v[22:23], v[10:11], v[188:189], v[22:23] op_sel_hi:[1,0,1]
	v_pk_fma_f32 v[0:1], v[12:13], v[188:189], v[0:1] op_sel_hi:[1,0,1]
	v_pk_fma_f32 v[2:3], v[14:15], v[188:189], v[2:3] op_sel_hi:[1,0,1]
	s_add_i32 s45, s66, 1
	v_readlane_b32 s44, v154, s45
	s_lshl_b32 s44, s44, 10
	s_add_u32 s46, s92, s44
	s_addc_u32 s47, s93, 0
	global_load_dwordx4 v[44:47], v216, s[46:47]
	s_waitcnt vmcnt(15)
	v_cvt_scalef32_pk_f32_fp4 v[8:9], v48, 1.0
	v_cvt_scalef32_pk_f32_fp4 v[10:11], v48, 1.0 op_sel:[1,0,0]
	v_cvt_scalef32_pk_f32_fp4 v[12:13], v48, 1.0 op_sel:[0,1,0]
	v_cvt_scalef32_pk_f32_fp4 v[14:15], v48, 1.0 op_sel:[1,1,0]
	v_cvt_scalef32_pk_f32_fp4 v[16:17], v49, 1.0
	v_cvt_scalef32_pk_f32_fp4 v[18:19], v49, 1.0 op_sel:[1,0,0]
	v_cvt_scalef32_pk_f32_fp4 v[64:65], v49, 1.0 op_sel:[0,1,0]
	v_cvt_scalef32_pk_f32_fp4 v[66:67], v49, 1.0 op_sel:[1,1,0]
	v_pk_fma_f32 v[24:25], v[8:9], v[188:189], v[24:25] op_sel:[0,1,0]
	v_pk_fma_f32 v[26:27], v[10:11], v[188:189], v[26:27] op_sel:[0,1,0]
	v_pk_fma_f32 v[40:41], v[12:13], v[188:189], v[40:41] op_sel:[0,1,0]
	v_pk_fma_f32 v[42:43], v[14:15], v[188:189], v[42:43] op_sel:[0,1,0]
	v_cvt_scalef32_pk_f32_fp4 v[68:69], v50, 1.0
	v_cvt_scalef32_pk_f32_fp4 v[70:71], v50, 1.0 op_sel:[1,0,0]
	v_cvt_scalef32_pk_f32_fp4 v[72:73], v50, 1.0 op_sel:[0,1,0]
	v_cvt_scalef32_pk_f32_fp4 v[74:75], v50, 1.0 op_sel:[1,1,0]
	v_pk_fma_f32 v[36:37], v[16:17], v[188:189], v[36:37] op_sel:[0,1,0]
	v_pk_fma_f32 v[38:39], v[18:19], v[188:189], v[38:39] op_sel:[0,1,0]
	v_pk_fma_f32 v[4:5], v[64:65], v[188:189], v[4:5] op_sel:[0,1,0]
	v_pk_fma_f32 v[6:7], v[66:67], v[188:189], v[6:7] op_sel:[0,1,0]
	v_cvt_scalef32_pk_f32_fp4 v[8:9], v51, 1.0
	v_cvt_scalef32_pk_f32_fp4 v[10:11], v51, 1.0 op_sel:[1,0,0]
	v_cvt_scalef32_pk_f32_fp4 v[12:13], v51, 1.0 op_sel:[0,1,0]
	v_cvt_scalef32_pk_f32_fp4 v[14:15], v51, 1.0 op_sel:[1,1,0]
	v_pk_fma_f32 v[32:33], v[68:69], v[188:189], v[32:33] op_sel:[0,1,0]
	v_pk_fma_f32 v[34:35], v[70:71], v[188:189], v[34:35] op_sel:[0,1,0]
	v_pk_fma_f32 v[28:29], v[72:73], v[188:189], v[28:29] op_sel:[0,1,0]
	v_pk_fma_f32 v[30:31], v[74:75], v[188:189], v[30:31] op_sel:[0,1,0]
	v_pk_fma_f32 v[20:21], v[8:9], v[188:189], v[20:21] op_sel:[0,1,0]
	v_pk_fma_f32 v[22:23], v[10:11], v[188:189], v[22:23] op_sel:[0,1,0]
	v_pk_fma_f32 v[0:1], v[12:13], v[188:189], v[0:1] op_sel:[0,1,0]
	v_pk_fma_f32 v[2:3], v[14:15], v[188:189], v[2:3] op_sel:[0,1,0]
	v_readlane_b32 s44, v155, s45
	s_lshl_b32 s44, s44, 10
	s_add_u32 s46, s92, s44
	s_addc_u32 s47, s93, 0
	global_load_dwordx4 v[48:51], v216, s[46:47]
	s_waitcnt vmcnt(15)
	v_cvt_scalef32_pk_f32_fp4 v[8:9], v52, 1.0
	v_cvt_scalef32_pk_f32_fp4 v[10:11], v52, 1.0 op_sel:[1,0,0]
	v_cvt_scalef32_pk_f32_fp4 v[12:13], v52, 1.0 op_sel:[0,1,0]
	v_cvt_scalef32_pk_f32_fp4 v[14:15], v52, 1.0 op_sel:[1,1,0]
	v_cvt_scalef32_pk_f32_fp4 v[16:17], v53, 1.0
	v_cvt_scalef32_pk_f32_fp4 v[18:19], v53, 1.0 op_sel:[1,0,0]
	v_cvt_scalef32_pk_f32_fp4 v[64:65], v53, 1.0 op_sel:[0,1,0]
	v_cvt_scalef32_pk_f32_fp4 v[66:67], v53, 1.0 op_sel:[1,1,0]
	v_pk_fma_f32 v[24:25], v[8:9], v[190:191], v[24:25] op_sel_hi:[1,0,1]
	v_pk_fma_f32 v[26:27], v[10:11], v[190:191], v[26:27] op_sel_hi:[1,0,1]
	v_pk_fma_f32 v[40:41], v[12:13], v[190:191], v[40:41] op_sel_hi:[1,0,1]
	v_pk_fma_f32 v[42:43], v[14:15], v[190:191], v[42:43] op_sel_hi:[1,0,1]
	v_cvt_scalef32_pk_f32_fp4 v[68:69], v54, 1.0
	v_cvt_scalef32_pk_f32_fp4 v[70:71], v54, 1.0 op_sel:[1,0,0]
	v_cvt_scalef32_pk_f32_fp4 v[72:73], v54, 1.0 op_sel:[0,1,0]
	v_cvt_scalef32_pk_f32_fp4 v[74:75], v54, 1.0 op_sel:[1,1,0]
	v_pk_fma_f32 v[36:37], v[16:17], v[190:191], v[36:37] op_sel_hi:[1,0,1]
	v_pk_fma_f32 v[38:39], v[18:19], v[190:191], v[38:39] op_sel_hi:[1,0,1]
	v_pk_fma_f32 v[4:5], v[64:65], v[190:191], v[4:5] op_sel_hi:[1,0,1]
	v_pk_fma_f32 v[6:7], v[66:67], v[190:191], v[6:7] op_sel_hi:[1,0,1]
	v_cvt_scalef32_pk_f32_fp4 v[8:9], v55, 1.0
	v_cvt_scalef32_pk_f32_fp4 v[10:11], v55, 1.0 op_sel:[1,0,0]
	v_cvt_scalef32_pk_f32_fp4 v[12:13], v55, 1.0 op_sel:[0,1,0]
	v_cvt_scalef32_pk_f32_fp4 v[14:15], v55, 1.0 op_sel:[1,1,0]
	v_pk_fma_f32 v[32:33], v[68:69], v[190:191], v[32:33] op_sel_hi:[1,0,1]
	v_pk_fma_f32 v[34:35], v[70:71], v[190:191], v[34:35] op_sel_hi:[1,0,1]
	v_pk_fma_f32 v[28:29], v[72:73], v[190:191], v[28:29] op_sel_hi:[1,0,1]
	v_pk_fma_f32 v[30:31], v[74:75], v[190:191], v[30:31] op_sel_hi:[1,0,1]
	v_pk_fma_f32 v[20:21], v[8:9], v[190:191], v[20:21] op_sel_hi:[1,0,1]
	v_pk_fma_f32 v[22:23], v[10:11], v[190:191], v[22:23] op_sel_hi:[1,0,1]
	v_pk_fma_f32 v[0:1], v[12:13], v[190:191], v[0:1] op_sel_hi:[1,0,1]
	v_pk_fma_f32 v[2:3], v[14:15], v[190:191], v[2:3] op_sel_hi:[1,0,1]
	s_add_i32 s45, s66, 2
	v_readlane_b32 s44, v154, s45
	s_lshl_b32 s44, s44, 10
	s_add_u32 s46, s92, s44
	s_addc_u32 s47, s93, 0
	global_load_dwordx4 v[52:55], v216, s[46:47]
	s_waitcnt vmcnt(15)
	v_cvt_scalef32_pk_f32_fp4 v[8:9], v56, 1.0
	v_cvt_scalef32_pk_f32_fp4 v[10:11], v56, 1.0 op_sel:[1,0,0]
	v_cvt_scalef32_pk_f32_fp4 v[12:13], v56, 1.0 op_sel:[0,1,0]
	v_cvt_scalef32_pk_f32_fp4 v[14:15], v56, 1.0 op_sel:[1,1,0]
	v_cvt_scalef32_pk_f32_fp4 v[16:17], v57, 1.0
	v_cvt_scalef32_pk_f32_fp4 v[18:19], v57, 1.0 op_sel:[1,0,0]
	v_cvt_scalef32_pk_f32_fp4 v[64:65], v57, 1.0 op_sel:[0,1,0]
	v_cvt_scalef32_pk_f32_fp4 v[66:67], v57, 1.0 op_sel:[1,1,0]
	v_pk_fma_f32 v[24:25], v[8:9], v[190:191], v[24:25] op_sel:[0,1,0]
	v_pk_fma_f32 v[26:27], v[10:11], v[190:191], v[26:27] op_sel:[0,1,0]
	v_pk_fma_f32 v[40:41], v[12:13], v[190:191], v[40:41] op_sel:[0,1,0]
	v_pk_fma_f32 v[42:43], v[14:15], v[190:191], v[42:43] op_sel:[0,1,0]
	v_cvt_scalef32_pk_f32_fp4 v[68:69], v58, 1.0
	v_cvt_scalef32_pk_f32_fp4 v[70:71], v58, 1.0 op_sel:[1,0,0]
	v_cvt_scalef32_pk_f32_fp4 v[72:73], v58, 1.0 op_sel:[0,1,0]
	v_cvt_scalef32_pk_f32_fp4 v[74:75], v58, 1.0 op_sel:[1,1,0]
	v_pk_fma_f32 v[36:37], v[16:17], v[190:191], v[36:37] op_sel:[0,1,0]
	v_pk_fma_f32 v[38:39], v[18:19], v[190:191], v[38:39] op_sel:[0,1,0]
	v_pk_fma_f32 v[4:5], v[64:65], v[190:191], v[4:5] op_sel:[0,1,0]
	v_pk_fma_f32 v[6:7], v[66:67], v[190:191], v[6:7] op_sel:[0,1,0]
	v_cvt_scalef32_pk_f32_fp4 v[8:9], v59, 1.0
	v_cvt_scalef32_pk_f32_fp4 v[10:11], v59, 1.0 op_sel:[1,0,0]
	v_cvt_scalef32_pk_f32_fp4 v[12:13], v59, 1.0 op_sel:[0,1,0]
	v_cvt_scalef32_pk_f32_fp4 v[14:15], v59, 1.0 op_sel:[1,1,0]
	v_pk_fma_f32 v[32:33], v[68:69], v[190:191], v[32:33] op_sel:[0,1,0]
	v_pk_fma_f32 v[34:35], v[70:71], v[190:191], v[34:35] op_sel:[0,1,0]
	v_pk_fma_f32 v[28:29], v[72:73], v[190:191], v[28:29] op_sel:[0,1,0]
	v_pk_fma_f32 v[30:31], v[74:75], v[190:191], v[30:31] op_sel:[0,1,0]
	v_pk_fma_f32 v[20:21], v[8:9], v[190:191], v[20:21] op_sel:[0,1,0]
	v_pk_fma_f32 v[22:23], v[10:11], v[190:191], v[22:23] op_sel:[0,1,0]
	v_pk_fma_f32 v[0:1], v[12:13], v[190:191], v[0:1] op_sel:[0,1,0]
	v_pk_fma_f32 v[2:3], v[14:15], v[190:191], v[2:3] op_sel:[0,1,0]
	v_readlane_b32 s44, v155, s45
	s_lshl_b32 s44, s44, 10
	s_add_u32 s46, s92, s44
	s_addc_u32 s47, s93, 0
	global_load_dwordx4 v[56:59], v216, s[46:47]
	ds_read_b128 v[188:191], v131 offset:64
	s_waitcnt vmcnt(15) lgkmcnt(3)
	v_cvt_scalef32_pk_f32_fp4 v[8:9], v60, 1.0
	v_cvt_scalef32_pk_f32_fp4 v[10:11], v60, 1.0 op_sel:[1,0,0]
	v_cvt_scalef32_pk_f32_fp4 v[12:13], v60, 1.0 op_sel:[0,1,0]
	v_cvt_scalef32_pk_f32_fp4 v[14:15], v60, 1.0 op_sel:[1,1,0]
	v_cvt_scalef32_pk_f32_fp4 v[16:17], v61, 1.0
	v_cvt_scalef32_pk_f32_fp4 v[18:19], v61, 1.0 op_sel:[1,0,0]
	v_cvt_scalef32_pk_f32_fp4 v[64:65], v61, 1.0 op_sel:[0,1,0]
	v_cvt_scalef32_pk_f32_fp4 v[66:67], v61, 1.0 op_sel:[1,1,0]
	v_pk_fma_f32 v[24:25], v[8:9], v[192:193], v[24:25] op_sel_hi:[1,0,1]
	v_pk_fma_f32 v[26:27], v[10:11], v[192:193], v[26:27] op_sel_hi:[1,0,1]
	v_pk_fma_f32 v[40:41], v[12:13], v[192:193], v[40:41] op_sel_hi:[1,0,1]
	v_pk_fma_f32 v[42:43], v[14:15], v[192:193], v[42:43] op_sel_hi:[1,0,1]
	v_cvt_scalef32_pk_f32_fp4 v[68:69], v62, 1.0
	v_cvt_scalef32_pk_f32_fp4 v[70:71], v62, 1.0 op_sel:[1,0,0]
	v_cvt_scalef32_pk_f32_fp4 v[72:73], v62, 1.0 op_sel:[0,1,0]
	v_cvt_scalef32_pk_f32_fp4 v[74:75], v62, 1.0 op_sel:[1,1,0]
	v_pk_fma_f32 v[36:37], v[16:17], v[192:193], v[36:37] op_sel_hi:[1,0,1]
	v_pk_fma_f32 v[38:39], v[18:19], v[192:193], v[38:39] op_sel_hi:[1,0,1]
	v_pk_fma_f32 v[4:5], v[64:65], v[192:193], v[4:5] op_sel_hi:[1,0,1]
	v_pk_fma_f32 v[6:7], v[66:67], v[192:193], v[6:7] op_sel_hi:[1,0,1]
	v_cvt_scalef32_pk_f32_fp4 v[8:9], v63, 1.0
	v_cvt_scalef32_pk_f32_fp4 v[10:11], v63, 1.0 op_sel:[1,0,0]
	v_cvt_scalef32_pk_f32_fp4 v[12:13], v63, 1.0 op_sel:[0,1,0]
	v_cvt_scalef32_pk_f32_fp4 v[14:15], v63, 1.0 op_sel:[1,1,0]
	v_pk_fma_f32 v[32:33], v[68:69], v[192:193], v[32:33] op_sel_hi:[1,0,1]
	v_pk_fma_f32 v[34:35], v[70:71], v[192:193], v[34:35] op_sel_hi:[1,0,1]
	v_pk_fma_f32 v[28:29], v[72:73], v[192:193], v[28:29] op_sel_hi:[1,0,1]
	v_pk_fma_f32 v[30:31], v[74:75], v[192:193], v[30:31] op_sel_hi:[1,0,1]
	v_pk_fma_f32 v[20:21], v[8:9], v[192:193], v[20:21] op_sel_hi:[1,0,1]
	v_pk_fma_f32 v[22:23], v[10:11], v[192:193], v[22:23] op_sel_hi:[1,0,1]
	v_pk_fma_f32 v[0:1], v[12:13], v[192:193], v[0:1] op_sel_hi:[1,0,1]
	v_pk_fma_f32 v[2:3], v[14:15], v[192:193], v[2:3] op_sel_hi:[1,0,1]
	s_add_i32 s45, s66, 3
	v_readlane_b32 s44, v154, s45
	s_lshl_b32 s44, s44, 10
	s_add_u32 s46, s92, s44
	s_addc_u32 s47, s93, 0
	global_load_dwordx4 v[60:63], v216, s[46:47]
	s_waitcnt vmcnt(15)
	v_cvt_scalef32_pk_f32_fp4 v[8:9], v76, 1.0
	v_cvt_scalef32_pk_f32_fp4 v[10:11], v76, 1.0 op_sel:[1,0,0]
	v_cvt_scalef32_pk_f32_fp4 v[12:13], v76, 1.0 op_sel:[0,1,0]
	v_cvt_scalef32_pk_f32_fp4 v[14:15], v76, 1.0 op_sel:[1,1,0]
	v_cvt_scalef32_pk_f32_fp4 v[16:17], v77, 1.0
	v_cvt_scalef32_pk_f32_fp4 v[18:19], v77, 1.0 op_sel:[1,0,0]
	v_cvt_scalef32_pk_f32_fp4 v[64:65], v77, 1.0 op_sel:[0,1,0]
	v_cvt_scalef32_pk_f32_fp4 v[66:67], v77, 1.0 op_sel:[1,1,0]
	v_pk_fma_f32 v[24:25], v[8:9], v[192:193], v[24:25] op_sel:[0,1,0]
	v_pk_fma_f32 v[26:27], v[10:11], v[192:193], v[26:27] op_sel:[0,1,0]
	v_pk_fma_f32 v[40:41], v[12:13], v[192:193], v[40:41] op_sel:[0,1,0]
	v_pk_fma_f32 v[42:43], v[14:15], v[192:193], v[42:43] op_sel:[0,1,0]
	v_cvt_scalef32_pk_f32_fp4 v[68:69], v78, 1.0
	v_cvt_scalef32_pk_f32_fp4 v[70:71], v78, 1.0 op_sel:[1,0,0]
	v_cvt_scalef32_pk_f32_fp4 v[72:73], v78, 1.0 op_sel:[0,1,0]
	v_cvt_scalef32_pk_f32_fp4 v[74:75], v78, 1.0 op_sel:[1,1,0]
	v_pk_fma_f32 v[36:37], v[16:17], v[192:193], v[36:37] op_sel:[0,1,0]
	v_pk_fma_f32 v[38:39], v[18:19], v[192:193], v[38:39] op_sel:[0,1,0]
	v_pk_fma_f32 v[4:5], v[64:65], v[192:193], v[4:5] op_sel:[0,1,0]
	v_pk_fma_f32 v[6:7], v[66:67], v[192:193], v[6:7] op_sel:[0,1,0]
	v_cvt_scalef32_pk_f32_fp4 v[8:9], v79, 1.0
	v_cvt_scalef32_pk_f32_fp4 v[10:11], v79, 1.0 op_sel:[1,0,0]
	v_cvt_scalef32_pk_f32_fp4 v[12:13], v79, 1.0 op_sel:[0,1,0]
	v_cvt_scalef32_pk_f32_fp4 v[14:15], v79, 1.0 op_sel:[1,1,0]
	v_pk_fma_f32 v[32:33], v[68:69], v[192:193], v[32:33] op_sel:[0,1,0]
	v_pk_fma_f32 v[34:35], v[70:71], v[192:193], v[34:35] op_sel:[0,1,0]
	v_pk_fma_f32 v[28:29], v[72:73], v[192:193], v[28:29] op_sel:[0,1,0]
	v_pk_fma_f32 v[30:31], v[74:75], v[192:193], v[30:31] op_sel:[0,1,0]
	v_pk_fma_f32 v[20:21], v[8:9], v[192:193], v[20:21] op_sel:[0,1,0]
	v_pk_fma_f32 v[22:23], v[10:11], v[192:193], v[22:23] op_sel:[0,1,0]
	v_pk_fma_f32 v[0:1], v[12:13], v[192:193], v[0:1] op_sel:[0,1,0]
	v_pk_fma_f32 v[2:3], v[14:15], v[192:193], v[2:3] op_sel:[0,1,0]
	v_readlane_b32 s44, v155, s45
	s_lshl_b32 s44, s44, 10
	s_add_u32 s46, s92, s44
	s_addc_u32 s47, s93, 0
	global_load_dwordx4 v[76:79], v216, s[46:47]
	s_waitcnt vmcnt(15)
	v_cvt_scalef32_pk_f32_fp4 v[8:9], v80, 1.0
	v_cvt_scalef32_pk_f32_fp4 v[10:11], v80, 1.0 op_sel:[1,0,0]
	v_cvt_scalef32_pk_f32_fp4 v[12:13], v80, 1.0 op_sel:[0,1,0]
	v_cvt_scalef32_pk_f32_fp4 v[14:15], v80, 1.0 op_sel:[1,1,0]
	v_cvt_scalef32_pk_f32_fp4 v[16:17], v81, 1.0
	v_cvt_scalef32_pk_f32_fp4 v[18:19], v81, 1.0 op_sel:[1,0,0]
	v_cvt_scalef32_pk_f32_fp4 v[64:65], v81, 1.0 op_sel:[0,1,0]
	v_cvt_scalef32_pk_f32_fp4 v[66:67], v81, 1.0 op_sel:[1,1,0]
	v_pk_fma_f32 v[24:25], v[8:9], v[194:195], v[24:25] op_sel_hi:[1,0,1]
	v_pk_fma_f32 v[26:27], v[10:11], v[194:195], v[26:27] op_sel_hi:[1,0,1]
	v_pk_fma_f32 v[40:41], v[12:13], v[194:195], v[40:41] op_sel_hi:[1,0,1]
	v_pk_fma_f32 v[42:43], v[14:15], v[194:195], v[42:43] op_sel_hi:[1,0,1]
	v_cvt_scalef32_pk_f32_fp4 v[68:69], v82, 1.0
	v_cvt_scalef32_pk_f32_fp4 v[70:71], v82, 1.0 op_sel:[1,0,0]
	v_cvt_scalef32_pk_f32_fp4 v[72:73], v82, 1.0 op_sel:[0,1,0]
	v_cvt_scalef32_pk_f32_fp4 v[74:75], v82, 1.0 op_sel:[1,1,0]
	v_pk_fma_f32 v[36:37], v[16:17], v[194:195], v[36:37] op_sel_hi:[1,0,1]
	v_pk_fma_f32 v[38:39], v[18:19], v[194:195], v[38:39] op_sel_hi:[1,0,1]
	v_pk_fma_f32 v[4:5], v[64:65], v[194:195], v[4:5] op_sel_hi:[1,0,1]
	v_pk_fma_f32 v[6:7], v[66:67], v[194:195], v[6:7] op_sel_hi:[1,0,1]
	v_cvt_scalef32_pk_f32_fp4 v[8:9], v83, 1.0
	v_cvt_scalef32_pk_f32_fp4 v[10:11], v83, 1.0 op_sel:[1,0,0]
	v_cvt_scalef32_pk_f32_fp4 v[12:13], v83, 1.0 op_sel:[0,1,0]
	v_cvt_scalef32_pk_f32_fp4 v[14:15], v83, 1.0 op_sel:[1,1,0]
	v_pk_fma_f32 v[32:33], v[68:69], v[194:195], v[32:33] op_sel_hi:[1,0,1]
	v_pk_fma_f32 v[34:35], v[70:71], v[194:195], v[34:35] op_sel_hi:[1,0,1]
	v_pk_fma_f32 v[28:29], v[72:73], v[194:195], v[28:29] op_sel_hi:[1,0,1]
	v_pk_fma_f32 v[30:31], v[74:75], v[194:195], v[30:31] op_sel_hi:[1,0,1]
	v_pk_fma_f32 v[20:21], v[8:9], v[194:195], v[20:21] op_sel_hi:[1,0,1]
	v_pk_fma_f32 v[22:23], v[10:11], v[194:195], v[22:23] op_sel_hi:[1,0,1]
	v_pk_fma_f32 v[0:1], v[12:13], v[194:195], v[0:1] op_sel_hi:[1,0,1]
	v_pk_fma_f32 v[2:3], v[14:15], v[194:195], v[2:3] op_sel_hi:[1,0,1]
	s_add_i32 s45, s66, 4
	v_readlane_b32 s44, v154, s45
	s_lshl_b32 s44, s44, 10
	s_add_u32 s46, s92, s44
	s_addc_u32 s47, s93, 0
	global_load_dwordx4 v[80:83], v216, s[46:47]
	s_waitcnt vmcnt(15)
	v_cvt_scalef32_pk_f32_fp4 v[8:9], v84, 1.0
	v_cvt_scalef32_pk_f32_fp4 v[10:11], v84, 1.0 op_sel:[1,0,0]
	v_cvt_scalef32_pk_f32_fp4 v[12:13], v84, 1.0 op_sel:[0,1,0]
	v_cvt_scalef32_pk_f32_fp4 v[14:15], v84, 1.0 op_sel:[1,1,0]
	v_cvt_scalef32_pk_f32_fp4 v[16:17], v85, 1.0
	v_cvt_scalef32_pk_f32_fp4 v[18:19], v85, 1.0 op_sel:[1,0,0]
	v_cvt_scalef32_pk_f32_fp4 v[64:65], v85, 1.0 op_sel:[0,1,0]
	v_cvt_scalef32_pk_f32_fp4 v[66:67], v85, 1.0 op_sel:[1,1,0]
	v_pk_fma_f32 v[24:25], v[8:9], v[194:195], v[24:25] op_sel:[0,1,0]
	v_pk_fma_f32 v[26:27], v[10:11], v[194:195], v[26:27] op_sel:[0,1,0]
	v_pk_fma_f32 v[40:41], v[12:13], v[194:195], v[40:41] op_sel:[0,1,0]
	v_pk_fma_f32 v[42:43], v[14:15], v[194:195], v[42:43] op_sel:[0,1,0]
	v_cvt_scalef32_pk_f32_fp4 v[68:69], v86, 1.0
	v_cvt_scalef32_pk_f32_fp4 v[70:71], v86, 1.0 op_sel:[1,0,0]
	v_cvt_scalef32_pk_f32_fp4 v[72:73], v86, 1.0 op_sel:[0,1,0]
	v_cvt_scalef32_pk_f32_fp4 v[74:75], v86, 1.0 op_sel:[1,1,0]
	v_pk_fma_f32 v[36:37], v[16:17], v[194:195], v[36:37] op_sel:[0,1,0]
	v_pk_fma_f32 v[38:39], v[18:19], v[194:195], v[38:39] op_sel:[0,1,0]
	v_pk_fma_f32 v[4:5], v[64:65], v[194:195], v[4:5] op_sel:[0,1,0]
	v_pk_fma_f32 v[6:7], v[66:67], v[194:195], v[6:7] op_sel:[0,1,0]
	v_cvt_scalef32_pk_f32_fp4 v[8:9], v87, 1.0
	v_cvt_scalef32_pk_f32_fp4 v[10:11], v87, 1.0 op_sel:[1,0,0]
	v_cvt_scalef32_pk_f32_fp4 v[12:13], v87, 1.0 op_sel:[0,1,0]
	v_cvt_scalef32_pk_f32_fp4 v[14:15], v87, 1.0 op_sel:[1,1,0]
	v_pk_fma_f32 v[32:33], v[68:69], v[194:195], v[32:33] op_sel:[0,1,0]
	v_pk_fma_f32 v[34:35], v[70:71], v[194:195], v[34:35] op_sel:[0,1,0]
	v_pk_fma_f32 v[28:29], v[72:73], v[194:195], v[28:29] op_sel:[0,1,0]
	v_pk_fma_f32 v[30:31], v[74:75], v[194:195], v[30:31] op_sel:[0,1,0]
	v_pk_fma_f32 v[20:21], v[8:9], v[194:195], v[20:21] op_sel:[0,1,0]
	v_pk_fma_f32 v[22:23], v[10:11], v[194:195], v[22:23] op_sel:[0,1,0]
	v_pk_fma_f32 v[0:1], v[12:13], v[194:195], v[0:1] op_sel:[0,1,0]
	v_pk_fma_f32 v[2:3], v[14:15], v[194:195], v[2:3] op_sel:[0,1,0]
	v_readlane_b32 s44, v155, s45
	s_lshl_b32 s44, s44, 10
	s_add_u32 s46, s92, s44
	s_addc_u32 s47, s93, 0
	global_load_dwordx4 v[84:87], v216, s[46:47]
	ds_read_b128 v[192:195], v131 offset:80
	s_waitcnt vmcnt(15) lgkmcnt(3)
	v_cvt_scalef32_pk_f32_fp4 v[8:9], v88, 1.0
	v_cvt_scalef32_pk_f32_fp4 v[10:11], v88, 1.0 op_sel:[1,0,0]
	v_cvt_scalef32_pk_f32_fp4 v[12:13], v88, 1.0 op_sel:[0,1,0]
	v_cvt_scalef32_pk_f32_fp4 v[14:15], v88, 1.0 op_sel:[1,1,0]
	v_cvt_scalef32_pk_f32_fp4 v[16:17], v89, 1.0
	v_cvt_scalef32_pk_f32_fp4 v[18:19], v89, 1.0 op_sel:[1,0,0]
	v_cvt_scalef32_pk_f32_fp4 v[64:65], v89, 1.0 op_sel:[0,1,0]
	v_cvt_scalef32_pk_f32_fp4 v[66:67], v89, 1.0 op_sel:[1,1,0]
	v_pk_fma_f32 v[24:25], v[8:9], v[240:241], v[24:25] op_sel_hi:[1,0,1]
	v_pk_fma_f32 v[26:27], v[10:11], v[240:241], v[26:27] op_sel_hi:[1,0,1]
	v_pk_fma_f32 v[40:41], v[12:13], v[240:241], v[40:41] op_sel_hi:[1,0,1]
	v_pk_fma_f32 v[42:43], v[14:15], v[240:241], v[42:43] op_sel_hi:[1,0,1]
	v_cvt_scalef32_pk_f32_fp4 v[68:69], v90, 1.0
	v_cvt_scalef32_pk_f32_fp4 v[70:71], v90, 1.0 op_sel:[1,0,0]
	v_cvt_scalef32_pk_f32_fp4 v[72:73], v90, 1.0 op_sel:[0,1,0]
	v_cvt_scalef32_pk_f32_fp4 v[74:75], v90, 1.0 op_sel:[1,1,0]
	v_pk_fma_f32 v[36:37], v[16:17], v[240:241], v[36:37] op_sel_hi:[1,0,1]
	v_pk_fma_f32 v[38:39], v[18:19], v[240:241], v[38:39] op_sel_hi:[1,0,1]
	v_pk_fma_f32 v[4:5], v[64:65], v[240:241], v[4:5] op_sel_hi:[1,0,1]
	v_pk_fma_f32 v[6:7], v[66:67], v[240:241], v[6:7] op_sel_hi:[1,0,1]
	v_cvt_scalef32_pk_f32_fp4 v[8:9], v91, 1.0
	v_cvt_scalef32_pk_f32_fp4 v[10:11], v91, 1.0 op_sel:[1,0,0]
	v_cvt_scalef32_pk_f32_fp4 v[12:13], v91, 1.0 op_sel:[0,1,0]
	v_cvt_scalef32_pk_f32_fp4 v[14:15], v91, 1.0 op_sel:[1,1,0]
	v_pk_fma_f32 v[32:33], v[68:69], v[240:241], v[32:33] op_sel_hi:[1,0,1]
	v_pk_fma_f32 v[34:35], v[70:71], v[240:241], v[34:35] op_sel_hi:[1,0,1]
	v_pk_fma_f32 v[28:29], v[72:73], v[240:241], v[28:29] op_sel_hi:[1,0,1]
	v_pk_fma_f32 v[30:31], v[74:75], v[240:241], v[30:31] op_sel_hi:[1,0,1]
	v_pk_fma_f32 v[20:21], v[8:9], v[240:241], v[20:21] op_sel_hi:[1,0,1]
	v_pk_fma_f32 v[22:23], v[10:11], v[240:241], v[22:23] op_sel_hi:[1,0,1]
	v_pk_fma_f32 v[0:1], v[12:13], v[240:241], v[0:1] op_sel_hi:[1,0,1]
	v_pk_fma_f32 v[2:3], v[14:15], v[240:241], v[2:3] op_sel_hi:[1,0,1]
	s_add_i32 s45, s66, 5
	v_readlane_b32 s44, v154, s45
	s_lshl_b32 s44, s44, 10
	s_add_u32 s46, s92, s44
	s_addc_u32 s47, s93, 0
	global_load_dwordx4 v[88:91], v216, s[46:47]
	s_waitcnt vmcnt(15)
	v_cvt_scalef32_pk_f32_fp4 v[8:9], v92, 1.0
	v_cvt_scalef32_pk_f32_fp4 v[10:11], v92, 1.0 op_sel:[1,0,0]
	v_cvt_scalef32_pk_f32_fp4 v[12:13], v92, 1.0 op_sel:[0,1,0]
	v_cvt_scalef32_pk_f32_fp4 v[14:15], v92, 1.0 op_sel:[1,1,0]
	v_cvt_scalef32_pk_f32_fp4 v[16:17], v93, 1.0
	v_cvt_scalef32_pk_f32_fp4 v[18:19], v93, 1.0 op_sel:[1,0,0]
	v_cvt_scalef32_pk_f32_fp4 v[64:65], v93, 1.0 op_sel:[0,1,0]
	v_cvt_scalef32_pk_f32_fp4 v[66:67], v93, 1.0 op_sel:[1,1,0]
	v_pk_fma_f32 v[24:25], v[8:9], v[240:241], v[24:25] op_sel:[0,1,0]
	v_pk_fma_f32 v[26:27], v[10:11], v[240:241], v[26:27] op_sel:[0,1,0]
	v_pk_fma_f32 v[40:41], v[12:13], v[240:241], v[40:41] op_sel:[0,1,0]
	v_pk_fma_f32 v[42:43], v[14:15], v[240:241], v[42:43] op_sel:[0,1,0]
	v_cvt_scalef32_pk_f32_fp4 v[68:69], v94, 1.0
	v_cvt_scalef32_pk_f32_fp4 v[70:71], v94, 1.0 op_sel:[1,0,0]
	v_cvt_scalef32_pk_f32_fp4 v[72:73], v94, 1.0 op_sel:[0,1,0]
	v_cvt_scalef32_pk_f32_fp4 v[74:75], v94, 1.0 op_sel:[1,1,0]
	v_pk_fma_f32 v[36:37], v[16:17], v[240:241], v[36:37] op_sel:[0,1,0]
	v_pk_fma_f32 v[38:39], v[18:19], v[240:241], v[38:39] op_sel:[0,1,0]
	v_pk_fma_f32 v[4:5], v[64:65], v[240:241], v[4:5] op_sel:[0,1,0]
	v_pk_fma_f32 v[6:7], v[66:67], v[240:241], v[6:7] op_sel:[0,1,0]
	v_cvt_scalef32_pk_f32_fp4 v[8:9], v95, 1.0
	v_cvt_scalef32_pk_f32_fp4 v[10:11], v95, 1.0 op_sel:[1,0,0]
	v_cvt_scalef32_pk_f32_fp4 v[12:13], v95, 1.0 op_sel:[0,1,0]
	v_cvt_scalef32_pk_f32_fp4 v[14:15], v95, 1.0 op_sel:[1,1,0]
	v_pk_fma_f32 v[32:33], v[68:69], v[240:241], v[32:33] op_sel:[0,1,0]
	v_pk_fma_f32 v[34:35], v[70:71], v[240:241], v[34:35] op_sel:[0,1,0]
	v_pk_fma_f32 v[28:29], v[72:73], v[240:241], v[28:29] op_sel:[0,1,0]
	v_pk_fma_f32 v[30:31], v[74:75], v[240:241], v[30:31] op_sel:[0,1,0]
	v_pk_fma_f32 v[20:21], v[8:9], v[240:241], v[20:21] op_sel:[0,1,0]
	v_pk_fma_f32 v[22:23], v[10:11], v[240:241], v[22:23] op_sel:[0,1,0]
	v_pk_fma_f32 v[0:1], v[12:13], v[240:241], v[0:1] op_sel:[0,1,0]
	v_pk_fma_f32 v[2:3], v[14:15], v[240:241], v[2:3] op_sel:[0,1,0]
	v_readlane_b32 s44, v155, s45
	s_lshl_b32 s44, s44, 10
	s_add_u32 s46, s92, s44
	s_addc_u32 s47, s93, 0
	global_load_dwordx4 v[92:95], v216, s[46:47]
	s_waitcnt vmcnt(15)
	v_cvt_scalef32_pk_f32_fp4 v[8:9], v96, 1.0
	v_cvt_scalef32_pk_f32_fp4 v[10:11], v96, 1.0 op_sel:[1,0,0]
	v_cvt_scalef32_pk_f32_fp4 v[12:13], v96, 1.0 op_sel:[0,1,0]
	v_cvt_scalef32_pk_f32_fp4 v[14:15], v96, 1.0 op_sel:[1,1,0]
	v_cvt_scalef32_pk_f32_fp4 v[16:17], v97, 1.0
	v_cvt_scalef32_pk_f32_fp4 v[18:19], v97, 1.0 op_sel:[1,0,0]
	v_cvt_scalef32_pk_f32_fp4 v[64:65], v97, 1.0 op_sel:[0,1,0]
	v_cvt_scalef32_pk_f32_fp4 v[66:67], v97, 1.0 op_sel:[1,1,0]
	v_pk_fma_f32 v[24:25], v[8:9], v[242:243], v[24:25] op_sel_hi:[1,0,1]
	v_pk_fma_f32 v[26:27], v[10:11], v[242:243], v[26:27] op_sel_hi:[1,0,1]
	v_pk_fma_f32 v[40:41], v[12:13], v[242:243], v[40:41] op_sel_hi:[1,0,1]
	v_pk_fma_f32 v[42:43], v[14:15], v[242:243], v[42:43] op_sel_hi:[1,0,1]
	v_cvt_scalef32_pk_f32_fp4 v[68:69], v98, 1.0
	v_cvt_scalef32_pk_f32_fp4 v[70:71], v98, 1.0 op_sel:[1,0,0]
	v_cvt_scalef32_pk_f32_fp4 v[72:73], v98, 1.0 op_sel:[0,1,0]
	v_cvt_scalef32_pk_f32_fp4 v[74:75], v98, 1.0 op_sel:[1,1,0]
	v_pk_fma_f32 v[36:37], v[16:17], v[242:243], v[36:37] op_sel_hi:[1,0,1]
	v_pk_fma_f32 v[38:39], v[18:19], v[242:243], v[38:39] op_sel_hi:[1,0,1]
	v_pk_fma_f32 v[4:5], v[64:65], v[242:243], v[4:5] op_sel_hi:[1,0,1]
	v_pk_fma_f32 v[6:7], v[66:67], v[242:243], v[6:7] op_sel_hi:[1,0,1]
	v_cvt_scalef32_pk_f32_fp4 v[8:9], v99, 1.0
	v_cvt_scalef32_pk_f32_fp4 v[10:11], v99, 1.0 op_sel:[1,0,0]
	v_cvt_scalef32_pk_f32_fp4 v[12:13], v99, 1.0 op_sel:[0,1,0]
	v_cvt_scalef32_pk_f32_fp4 v[14:15], v99, 1.0 op_sel:[1,1,0]
	v_pk_fma_f32 v[32:33], v[68:69], v[242:243], v[32:33] op_sel_hi:[1,0,1]
	v_pk_fma_f32 v[34:35], v[70:71], v[242:243], v[34:35] op_sel_hi:[1,0,1]
	v_pk_fma_f32 v[28:29], v[72:73], v[242:243], v[28:29] op_sel_hi:[1,0,1]
	v_pk_fma_f32 v[30:31], v[74:75], v[242:243], v[30:31] op_sel_hi:[1,0,1]
	v_pk_fma_f32 v[20:21], v[8:9], v[242:243], v[20:21] op_sel_hi:[1,0,1]
	v_pk_fma_f32 v[22:23], v[10:11], v[242:243], v[22:23] op_sel_hi:[1,0,1]
	v_pk_fma_f32 v[0:1], v[12:13], v[242:243], v[0:1] op_sel_hi:[1,0,1]
	v_pk_fma_f32 v[2:3], v[14:15], v[242:243], v[2:3] op_sel_hi:[1,0,1]
	s_add_i32 s45, s66, 6
	v_readlane_b32 s44, v154, s45
	s_lshl_b32 s44, s44, 10
	s_add_u32 s46, s92, s44
	s_addc_u32 s47, s93, 0
	global_load_dwordx4 v[96:99], v216, s[46:47]
	s_waitcnt vmcnt(15)
	v_cvt_scalef32_pk_f32_fp4 v[8:9], v100, 1.0
	v_cvt_scalef32_pk_f32_fp4 v[10:11], v100, 1.0 op_sel:[1,0,0]
	v_cvt_scalef32_pk_f32_fp4 v[12:13], v100, 1.0 op_sel:[0,1,0]
	v_cvt_scalef32_pk_f32_fp4 v[14:15], v100, 1.0 op_sel:[1,1,0]
	v_cvt_scalef32_pk_f32_fp4 v[16:17], v101, 1.0
	v_cvt_scalef32_pk_f32_fp4 v[18:19], v101, 1.0 op_sel:[1,0,0]
	v_cvt_scalef32_pk_f32_fp4 v[64:65], v101, 1.0 op_sel:[0,1,0]
	v_cvt_scalef32_pk_f32_fp4 v[66:67], v101, 1.0 op_sel:[1,1,0]
	v_pk_fma_f32 v[24:25], v[8:9], v[242:243], v[24:25] op_sel:[0,1,0]
	v_pk_fma_f32 v[26:27], v[10:11], v[242:243], v[26:27] op_sel:[0,1,0]
	v_pk_fma_f32 v[40:41], v[12:13], v[242:243], v[40:41] op_sel:[0,1,0]
	v_pk_fma_f32 v[42:43], v[14:15], v[242:243], v[42:43] op_sel:[0,1,0]
	v_cvt_scalef32_pk_f32_fp4 v[68:69], v102, 1.0
	v_cvt_scalef32_pk_f32_fp4 v[70:71], v102, 1.0 op_sel:[1,0,0]
	v_cvt_scalef32_pk_f32_fp4 v[72:73], v102, 1.0 op_sel:[0,1,0]
	v_cvt_scalef32_pk_f32_fp4 v[74:75], v102, 1.0 op_sel:[1,1,0]
	v_pk_fma_f32 v[36:37], v[16:17], v[242:243], v[36:37] op_sel:[0,1,0]
	v_pk_fma_f32 v[38:39], v[18:19], v[242:243], v[38:39] op_sel:[0,1,0]
	v_pk_fma_f32 v[4:5], v[64:65], v[242:243], v[4:5] op_sel:[0,1,0]
	v_pk_fma_f32 v[6:7], v[66:67], v[242:243], v[6:7] op_sel:[0,1,0]
	v_cvt_scalef32_pk_f32_fp4 v[8:9], v103, 1.0
	v_cvt_scalef32_pk_f32_fp4 v[10:11], v103, 1.0 op_sel:[1,0,0]
	v_cvt_scalef32_pk_f32_fp4 v[12:13], v103, 1.0 op_sel:[0,1,0]
	v_cvt_scalef32_pk_f32_fp4 v[14:15], v103, 1.0 op_sel:[1,1,0]
	v_pk_fma_f32 v[32:33], v[68:69], v[242:243], v[32:33] op_sel:[0,1,0]
	v_pk_fma_f32 v[34:35], v[70:71], v[242:243], v[34:35] op_sel:[0,1,0]
	v_pk_fma_f32 v[28:29], v[72:73], v[242:243], v[28:29] op_sel:[0,1,0]
	v_pk_fma_f32 v[30:31], v[74:75], v[242:243], v[30:31] op_sel:[0,1,0]
	v_pk_fma_f32 v[20:21], v[8:9], v[242:243], v[20:21] op_sel:[0,1,0]
	v_pk_fma_f32 v[22:23], v[10:11], v[242:243], v[22:23] op_sel:[0,1,0]
	v_pk_fma_f32 v[0:1], v[12:13], v[242:243], v[0:1] op_sel:[0,1,0]
	v_pk_fma_f32 v[2:3], v[14:15], v[242:243], v[2:3] op_sel:[0,1,0]
	v_readlane_b32 s44, v155, s45
	s_lshl_b32 s44, s44, 10
	s_add_u32 s46, s92, s44
	s_addc_u32 s47, s93, 0
	global_load_dwordx4 v[100:103], v216, s[46:47]
	ds_read_b128 v[240:243], v131 offset:96
	s_waitcnt vmcnt(15) lgkmcnt(3)
	v_cvt_scalef32_pk_f32_fp4 v[8:9], v172, 1.0
	v_cvt_scalef32_pk_f32_fp4 v[10:11], v172, 1.0 op_sel:[1,0,0]
	v_cvt_scalef32_pk_f32_fp4 v[12:13], v172, 1.0 op_sel:[0,1,0]
	v_cvt_scalef32_pk_f32_fp4 v[14:15], v172, 1.0 op_sel:[1,1,0]
	v_cvt_scalef32_pk_f32_fp4 v[16:17], v173, 1.0
	v_cvt_scalef32_pk_f32_fp4 v[18:19], v173, 1.0 op_sel:[1,0,0]
	v_cvt_scalef32_pk_f32_fp4 v[64:65], v173, 1.0 op_sel:[0,1,0]
	v_cvt_scalef32_pk_f32_fp4 v[66:67], v173, 1.0 op_sel:[1,1,0]
	v_pk_fma_f32 v[24:25], v[8:9], v[244:245], v[24:25] op_sel_hi:[1,0,1]
	v_pk_fma_f32 v[26:27], v[10:11], v[244:245], v[26:27] op_sel_hi:[1,0,1]
	v_pk_fma_f32 v[40:41], v[12:13], v[244:245], v[40:41] op_sel_hi:[1,0,1]
	v_pk_fma_f32 v[42:43], v[14:15], v[244:245], v[42:43] op_sel_hi:[1,0,1]
	v_cvt_scalef32_pk_f32_fp4 v[68:69], v174, 1.0
	v_cvt_scalef32_pk_f32_fp4 v[70:71], v174, 1.0 op_sel:[1,0,0]
	v_cvt_scalef32_pk_f32_fp4 v[72:73], v174, 1.0 op_sel:[0,1,0]
	v_cvt_scalef32_pk_f32_fp4 v[74:75], v174, 1.0 op_sel:[1,1,0]
	v_pk_fma_f32 v[36:37], v[16:17], v[244:245], v[36:37] op_sel_hi:[1,0,1]
	v_pk_fma_f32 v[38:39], v[18:19], v[244:245], v[38:39] op_sel_hi:[1,0,1]
	v_pk_fma_f32 v[4:5], v[64:65], v[244:245], v[4:5] op_sel_hi:[1,0,1]
	v_pk_fma_f32 v[6:7], v[66:67], v[244:245], v[6:7] op_sel_hi:[1,0,1]
	v_cvt_scalef32_pk_f32_fp4 v[8:9], v175, 1.0
	v_cvt_scalef32_pk_f32_fp4 v[10:11], v175, 1.0 op_sel:[1,0,0]
	v_cvt_scalef32_pk_f32_fp4 v[12:13], v175, 1.0 op_sel:[0,1,0]
	v_cvt_scalef32_pk_f32_fp4 v[14:15], v175, 1.0 op_sel:[1,1,0]
	v_pk_fma_f32 v[32:33], v[68:69], v[244:245], v[32:33] op_sel_hi:[1,0,1]
	v_pk_fma_f32 v[34:35], v[70:71], v[244:245], v[34:35] op_sel_hi:[1,0,1]
	v_pk_fma_f32 v[28:29], v[72:73], v[244:245], v[28:29] op_sel_hi:[1,0,1]
	v_pk_fma_f32 v[30:31], v[74:75], v[244:245], v[30:31] op_sel_hi:[1,0,1]
	v_pk_fma_f32 v[20:21], v[8:9], v[244:245], v[20:21] op_sel_hi:[1,0,1]
	v_pk_fma_f32 v[22:23], v[10:11], v[244:245], v[22:23] op_sel_hi:[1,0,1]
	v_pk_fma_f32 v[0:1], v[12:13], v[244:245], v[0:1] op_sel_hi:[1,0,1]
	v_pk_fma_f32 v[2:3], v[14:15], v[244:245], v[2:3] op_sel_hi:[1,0,1]
	s_add_i32 s45, s66, 7
	v_readlane_b32 s44, v154, s45
	s_lshl_b32 s44, s44, 10
	s_add_u32 s46, s92, s44
	s_addc_u32 s47, s93, 0
	global_load_dwordx4 v[172:175], v216, s[46:47]
	s_waitcnt vmcnt(15)
	v_cvt_scalef32_pk_f32_fp4 v[8:9], v176, 1.0
	v_cvt_scalef32_pk_f32_fp4 v[10:11], v176, 1.0 op_sel:[1,0,0]
	v_cvt_scalef32_pk_f32_fp4 v[12:13], v176, 1.0 op_sel:[0,1,0]
	v_cvt_scalef32_pk_f32_fp4 v[14:15], v176, 1.0 op_sel:[1,1,0]
	v_cvt_scalef32_pk_f32_fp4 v[16:17], v177, 1.0
	v_cvt_scalef32_pk_f32_fp4 v[18:19], v177, 1.0 op_sel:[1,0,0]
	v_cvt_scalef32_pk_f32_fp4 v[64:65], v177, 1.0 op_sel:[0,1,0]
	v_cvt_scalef32_pk_f32_fp4 v[66:67], v177, 1.0 op_sel:[1,1,0]
	v_pk_fma_f32 v[24:25], v[8:9], v[244:245], v[24:25] op_sel:[0,1,0]
	v_pk_fma_f32 v[26:27], v[10:11], v[244:245], v[26:27] op_sel:[0,1,0]
	v_pk_fma_f32 v[40:41], v[12:13], v[244:245], v[40:41] op_sel:[0,1,0]
	v_pk_fma_f32 v[42:43], v[14:15], v[244:245], v[42:43] op_sel:[0,1,0]
	v_cvt_scalef32_pk_f32_fp4 v[68:69], v178, 1.0
	v_cvt_scalef32_pk_f32_fp4 v[70:71], v178, 1.0 op_sel:[1,0,0]
	v_cvt_scalef32_pk_f32_fp4 v[72:73], v178, 1.0 op_sel:[0,1,0]
	v_cvt_scalef32_pk_f32_fp4 v[74:75], v178, 1.0 op_sel:[1,1,0]
	v_pk_fma_f32 v[36:37], v[16:17], v[244:245], v[36:37] op_sel:[0,1,0]
	v_pk_fma_f32 v[38:39], v[18:19], v[244:245], v[38:39] op_sel:[0,1,0]
	v_pk_fma_f32 v[4:5], v[64:65], v[244:245], v[4:5] op_sel:[0,1,0]
	v_pk_fma_f32 v[6:7], v[66:67], v[244:245], v[6:7] op_sel:[0,1,0]
	v_cvt_scalef32_pk_f32_fp4 v[8:9], v179, 1.0
	v_cvt_scalef32_pk_f32_fp4 v[10:11], v179, 1.0 op_sel:[1,0,0]
	v_cvt_scalef32_pk_f32_fp4 v[12:13], v179, 1.0 op_sel:[0,1,0]
	v_cvt_scalef32_pk_f32_fp4 v[14:15], v179, 1.0 op_sel:[1,1,0]
	v_pk_fma_f32 v[32:33], v[68:69], v[244:245], v[32:33] op_sel:[0,1,0]
	v_pk_fma_f32 v[34:35], v[70:71], v[244:245], v[34:35] op_sel:[0,1,0]
	v_pk_fma_f32 v[28:29], v[72:73], v[244:245], v[28:29] op_sel:[0,1,0]
	v_pk_fma_f32 v[30:31], v[74:75], v[244:245], v[30:31] op_sel:[0,1,0]
	v_pk_fma_f32 v[20:21], v[8:9], v[244:245], v[20:21] op_sel:[0,1,0]
	v_pk_fma_f32 v[22:23], v[10:11], v[244:245], v[22:23] op_sel:[0,1,0]
	v_pk_fma_f32 v[0:1], v[12:13], v[244:245], v[0:1] op_sel:[0,1,0]
	v_pk_fma_f32 v[2:3], v[14:15], v[244:245], v[2:3] op_sel:[0,1,0]
	v_readlane_b32 s44, v155, s45
	s_lshl_b32 s44, s44, 10
	s_add_u32 s46, s92, s44
	s_addc_u32 s47, s93, 0
	global_load_dwordx4 v[176:179], v216, s[46:47]
	s_waitcnt vmcnt(15)
	v_cvt_scalef32_pk_f32_fp4 v[8:9], v180, 1.0
	v_cvt_scalef32_pk_f32_fp4 v[10:11], v180, 1.0 op_sel:[1,0,0]
	v_cvt_scalef32_pk_f32_fp4 v[12:13], v180, 1.0 op_sel:[0,1,0]
	v_cvt_scalef32_pk_f32_fp4 v[14:15], v180, 1.0 op_sel:[1,1,0]
	v_cvt_scalef32_pk_f32_fp4 v[16:17], v181, 1.0
	v_cvt_scalef32_pk_f32_fp4 v[18:19], v181, 1.0 op_sel:[1,0,0]
	v_cvt_scalef32_pk_f32_fp4 v[64:65], v181, 1.0 op_sel:[0,1,0]
	v_cvt_scalef32_pk_f32_fp4 v[66:67], v181, 1.0 op_sel:[1,1,0]
	v_pk_fma_f32 v[24:25], v[8:9], v[246:247], v[24:25] op_sel_hi:[1,0,1]
	v_pk_fma_f32 v[26:27], v[10:11], v[246:247], v[26:27] op_sel_hi:[1,0,1]
	v_pk_fma_f32 v[40:41], v[12:13], v[246:247], v[40:41] op_sel_hi:[1,0,1]
	v_pk_fma_f32 v[42:43], v[14:15], v[246:247], v[42:43] op_sel_hi:[1,0,1]
	v_cvt_scalef32_pk_f32_fp4 v[68:69], v182, 1.0
	v_cvt_scalef32_pk_f32_fp4 v[70:71], v182, 1.0 op_sel:[1,0,0]
	v_cvt_scalef32_pk_f32_fp4 v[72:73], v182, 1.0 op_sel:[0,1,0]
	v_cvt_scalef32_pk_f32_fp4 v[74:75], v182, 1.0 op_sel:[1,1,0]
	v_pk_fma_f32 v[36:37], v[16:17], v[246:247], v[36:37] op_sel_hi:[1,0,1]
	v_pk_fma_f32 v[38:39], v[18:19], v[246:247], v[38:39] op_sel_hi:[1,0,1]
	v_pk_fma_f32 v[4:5], v[64:65], v[246:247], v[4:5] op_sel_hi:[1,0,1]
	v_pk_fma_f32 v[6:7], v[66:67], v[246:247], v[6:7] op_sel_hi:[1,0,1]
	v_cvt_scalef32_pk_f32_fp4 v[8:9], v183, 1.0
	v_cvt_scalef32_pk_f32_fp4 v[10:11], v183, 1.0 op_sel:[1,0,0]
	v_cvt_scalef32_pk_f32_fp4 v[12:13], v183, 1.0 op_sel:[0,1,0]
	v_cvt_scalef32_pk_f32_fp4 v[14:15], v183, 1.0 op_sel:[1,1,0]
	v_pk_fma_f32 v[32:33], v[68:69], v[246:247], v[32:33] op_sel_hi:[1,0,1]
	v_pk_fma_f32 v[34:35], v[70:71], v[246:247], v[34:35] op_sel_hi:[1,0,1]
	v_pk_fma_f32 v[28:29], v[72:73], v[246:247], v[28:29] op_sel_hi:[1,0,1]
	v_pk_fma_f32 v[30:31], v[74:75], v[246:247], v[30:31] op_sel_hi:[1,0,1]
	v_pk_fma_f32 v[20:21], v[8:9], v[246:247], v[20:21] op_sel_hi:[1,0,1]
	v_pk_fma_f32 v[22:23], v[10:11], v[246:247], v[22:23] op_sel_hi:[1,0,1]
	v_pk_fma_f32 v[0:1], v[12:13], v[246:247], v[0:1] op_sel_hi:[1,0,1]
	v_pk_fma_f32 v[2:3], v[14:15], v[246:247], v[2:3] op_sel_hi:[1,0,1]
	s_add_i32 s45, s66, 8
	v_readlane_b32 s44, v154, s45
	s_lshl_b32 s44, s44, 10
	s_add_u32 s46, s92, s44
	s_addc_u32 s47, s93, 0
	global_load_dwordx4 v[180:183], v216, s[46:47]
	s_waitcnt vmcnt(15)
	v_cvt_scalef32_pk_f32_fp4 v[8:9], v184, 1.0
	v_cvt_scalef32_pk_f32_fp4 v[10:11], v184, 1.0 op_sel:[1,0,0]
	v_cvt_scalef32_pk_f32_fp4 v[12:13], v184, 1.0 op_sel:[0,1,0]
	v_cvt_scalef32_pk_f32_fp4 v[14:15], v184, 1.0 op_sel:[1,1,0]
	v_cvt_scalef32_pk_f32_fp4 v[16:17], v185, 1.0
	v_cvt_scalef32_pk_f32_fp4 v[18:19], v185, 1.0 op_sel:[1,0,0]
	v_cvt_scalef32_pk_f32_fp4 v[64:65], v185, 1.0 op_sel:[0,1,0]
	v_cvt_scalef32_pk_f32_fp4 v[66:67], v185, 1.0 op_sel:[1,1,0]
	v_pk_fma_f32 v[24:25], v[8:9], v[246:247], v[24:25] op_sel:[0,1,0]
	v_pk_fma_f32 v[26:27], v[10:11], v[246:247], v[26:27] op_sel:[0,1,0]
	v_pk_fma_f32 v[40:41], v[12:13], v[246:247], v[40:41] op_sel:[0,1,0]
	v_pk_fma_f32 v[42:43], v[14:15], v[246:247], v[42:43] op_sel:[0,1,0]
	v_cvt_scalef32_pk_f32_fp4 v[68:69], v186, 1.0
	v_cvt_scalef32_pk_f32_fp4 v[70:71], v186, 1.0 op_sel:[1,0,0]
	v_cvt_scalef32_pk_f32_fp4 v[72:73], v186, 1.0 op_sel:[0,1,0]
	v_cvt_scalef32_pk_f32_fp4 v[74:75], v186, 1.0 op_sel:[1,1,0]
	v_pk_fma_f32 v[36:37], v[16:17], v[246:247], v[36:37] op_sel:[0,1,0]
	v_pk_fma_f32 v[38:39], v[18:19], v[246:247], v[38:39] op_sel:[0,1,0]
	v_pk_fma_f32 v[4:5], v[64:65], v[246:247], v[4:5] op_sel:[0,1,0]
	v_pk_fma_f32 v[6:7], v[66:67], v[246:247], v[6:7] op_sel:[0,1,0]
	v_cvt_scalef32_pk_f32_fp4 v[8:9], v187, 1.0
	v_cvt_scalef32_pk_f32_fp4 v[10:11], v187, 1.0 op_sel:[1,0,0]
	v_cvt_scalef32_pk_f32_fp4 v[12:13], v187, 1.0 op_sel:[0,1,0]
	v_cvt_scalef32_pk_f32_fp4 v[14:15], v187, 1.0 op_sel:[1,1,0]
	v_pk_fma_f32 v[32:33], v[68:69], v[246:247], v[32:33] op_sel:[0,1,0]
	v_pk_fma_f32 v[34:35], v[70:71], v[246:247], v[34:35] op_sel:[0,1,0]
	v_pk_fma_f32 v[28:29], v[72:73], v[246:247], v[28:29] op_sel:[0,1,0]
	v_pk_fma_f32 v[30:31], v[74:75], v[246:247], v[30:31] op_sel:[0,1,0]
	v_pk_fma_f32 v[20:21], v[8:9], v[246:247], v[20:21] op_sel:[0,1,0]
	v_pk_fma_f32 v[22:23], v[10:11], v[246:247], v[22:23] op_sel:[0,1,0]
	v_pk_fma_f32 v[0:1], v[12:13], v[246:247], v[0:1] op_sel:[0,1,0]
	v_pk_fma_f32 v[2:3], v[14:15], v[246:247], v[2:3] op_sel:[0,1,0]
	v_readlane_b32 s44, v155, s45
	s_lshl_b32 s44, s44, 10
	s_add_u32 s46, s92, s44
	s_addc_u32 s47, s93, 0
	global_load_dwordx4 v[184:187], v216, s[46:47]
	ds_read_b128 v[244:247], v131 offset:112
	s_add_i32 s65, s65, 16
	s_add_i32 s66, s66, 8
	v_add_u32_e32 v131, 64, v131
	s_cmpk_lt_u32 s65, 0x60
	s_cbranch_scc1 .Lp10v_loop
	s_waitcnt vmcnt(15) lgkmcnt(3)
	v_cvt_scalef32_pk_f32_fp4 v[8:9], v44, 1.0
	v_cvt_scalef32_pk_f32_fp4 v[10:11], v44, 1.0 op_sel:[1,0,0]
	v_cvt_scalef32_pk_f32_fp4 v[12:13], v44, 1.0 op_sel:[0,1,0]
	v_cvt_scalef32_pk_f32_fp4 v[14:15], v44, 1.0 op_sel:[1,1,0]
	v_cvt_scalef32_pk_f32_fp4 v[16:17], v45, 1.0
	v_cvt_scalef32_pk_f32_fp4 v[18:19], v45, 1.0 op_sel:[1,0,0]
	v_cvt_scalef32_pk_f32_fp4 v[64:65], v45, 1.0 op_sel:[0,1,0]
	v_cvt_scalef32_pk_f32_fp4 v[66:67], v45, 1.0 op_sel:[1,1,0]
	v_pk_fma_f32 v[24:25], v[8:9], v[188:189], v[24:25] op_sel_hi:[1,0,1]
	v_pk_fma_f32 v[26:27], v[10:11], v[188:189], v[26:27] op_sel_hi:[1,0,1]
	v_pk_fma_f32 v[40:41], v[12:13], v[188:189], v[40:41] op_sel_hi:[1,0,1]
	v_pk_fma_f32 v[42:43], v[14:15], v[188:189], v[42:43] op_sel_hi:[1,0,1]
	v_cvt_scalef32_pk_f32_fp4 v[68:69], v46, 1.0
	v_cvt_scalef32_pk_f32_fp4 v[70:71], v46, 1.0 op_sel:[1,0,0]
	v_cvt_scalef32_pk_f32_fp4 v[72:73], v46, 1.0 op_sel:[0,1,0]
	v_cvt_scalef32_pk_f32_fp4 v[74:75], v46, 1.0 op_sel:[1,1,0]
	v_pk_fma_f32 v[36:37], v[16:17], v[188:189], v[36:37] op_sel_hi:[1,0,1]
	v_pk_fma_f32 v[38:39], v[18:19], v[188:189], v[38:39] op_sel_hi:[1,0,1]
	v_pk_fma_f32 v[4:5], v[64:65], v[188:189], v[4:5] op_sel_hi:[1,0,1]
	v_pk_fma_f32 v[6:7], v[66:67], v[188:189], v[6:7] op_sel_hi:[1,0,1]
	v_cvt_scalef32_pk_f32_fp4 v[8:9], v47, 1.0
	v_cvt_scalef32_pk_f32_fp4 v[10:11], v47, 1.0 op_sel:[1,0,0]
	v_cvt_scalef32_pk_f32_fp4 v[12:13], v47, 1.0 op_sel:[0,1,0]
	v_cvt_scalef32_pk_f32_fp4 v[14:15], v47, 1.0 op_sel:[1,1,0]
	v_pk_fma_f32 v[32:33], v[68:69], v[188:189], v[32:33] op_sel_hi:[1,0,1]
	v_pk_fma_f32 v[34:35], v[70:71], v[188:189], v[34:35] op_sel_hi:[1,0,1]
	v_pk_fma_f32 v[28:29], v[72:73], v[188:189], v[28:29] op_sel_hi:[1,0,1]
	v_pk_fma_f32 v[30:31], v[74:75], v[188:189], v[30:31] op_sel_hi:[1,0,1]
	v_pk_fma_f32 v[20:21], v[8:9], v[188:189], v[20:21] op_sel_hi:[1,0,1]
	v_pk_fma_f32 v[22:23], v[10:11], v[188:189], v[22:23] op_sel_hi:[1,0,1]
	v_pk_fma_f32 v[0:1], v[12:13], v[188:189], v[0:1] op_sel_hi:[1,0,1]
	v_pk_fma_f32 v[2:3], v[14:15], v[188:189], v[2:3] op_sel_hi:[1,0,1]
	s_waitcnt vmcnt(14)
	v_cvt_scalef32_pk_f32_fp4 v[8:9], v48, 1.0
	v_cvt_scalef32_pk_f32_fp4 v[10:11], v48, 1.0 op_sel:[1,0,0]
	v_cvt_scalef32_pk_f32_fp4 v[12:13], v48, 1.0 op_sel:[0,1,0]
	v_cvt_scalef32_pk_f32_fp4 v[14:15], v48, 1.0 op_sel:[1,1,0]
	v_cvt_scalef32_pk_f32_fp4 v[16:17], v49, 1.0
	v_cvt_scalef32_pk_f32_fp4 v[18:19], v49, 1.0 op_sel:[1,0,0]
	v_cvt_scalef32_pk_f32_fp4 v[64:65], v49, 1.0 op_sel:[0,1,0]
	v_cvt_scalef32_pk_f32_fp4 v[66:67], v49, 1.0 op_sel:[1,1,0]
	v_pk_fma_f32 v[24:25], v[8:9], v[188:189], v[24:25] op_sel:[0,1,0]
	v_pk_fma_f32 v[26:27], v[10:11], v[188:189], v[26:27] op_sel:[0,1,0]
	v_pk_fma_f32 v[40:41], v[12:13], v[188:189], v[40:41] op_sel:[0,1,0]
	v_pk_fma_f32 v[42:43], v[14:15], v[188:189], v[42:43] op_sel:[0,1,0]
	v_cvt_scalef32_pk_f32_fp4 v[68:69], v50, 1.0
	v_cvt_scalef32_pk_f32_fp4 v[70:71], v50, 1.0 op_sel:[1,0,0]
	v_cvt_scalef32_pk_f32_fp4 v[72:73], v50, 1.0 op_sel:[0,1,0]
	v_cvt_scalef32_pk_f32_fp4 v[74:75], v50, 1.0 op_sel:[1,1,0]
	v_pk_fma_f32 v[36:37], v[16:17], v[188:189], v[36:37] op_sel:[0,1,0]
	v_pk_fma_f32 v[38:39], v[18:19], v[188:189], v[38:39] op_sel:[0,1,0]
	v_pk_fma_f32 v[4:5], v[64:65], v[188:189], v[4:5] op_sel:[0,1,0]
	v_pk_fma_f32 v[6:7], v[66:67], v[188:189], v[6:7] op_sel:[0,1,0]
	v_cvt_scalef32_pk_f32_fp4 v[8:9], v51, 1.0
	v_cvt_scalef32_pk_f32_fp4 v[10:11], v51, 1.0 op_sel:[1,0,0]
	v_cvt_scalef32_pk_f32_fp4 v[12:13], v51, 1.0 op_sel:[0,1,0]
	v_cvt_scalef32_pk_f32_fp4 v[14:15], v51, 1.0 op_sel:[1,1,0]
	v_pk_fma_f32 v[32:33], v[68:69], v[188:189], v[32:33] op_sel:[0,1,0]
	v_pk_fma_f32 v[34:35], v[70:71], v[188:189], v[34:35] op_sel:[0,1,0]
	v_pk_fma_f32 v[28:29], v[72:73], v[188:189], v[28:29] op_sel:[0,1,0]
	v_pk_fma_f32 v[30:31], v[74:75], v[188:189], v[30:31] op_sel:[0,1,0]
	v_pk_fma_f32 v[20:21], v[8:9], v[188:189], v[20:21] op_sel:[0,1,0]
	v_pk_fma_f32 v[22:23], v[10:11], v[188:189], v[22:23] op_sel:[0,1,0]
	v_pk_fma_f32 v[0:1], v[12:13], v[188:189], v[0:1] op_sel:[0,1,0]
	v_pk_fma_f32 v[2:3], v[14:15], v[188:189], v[2:3] op_sel:[0,1,0]
	s_waitcnt vmcnt(13)
	v_cvt_scalef32_pk_f32_fp4 v[8:9], v52, 1.0
	v_cvt_scalef32_pk_f32_fp4 v[10:11], v52, 1.0 op_sel:[1,0,0]
	v_cvt_scalef32_pk_f32_fp4 v[12:13], v52, 1.0 op_sel:[0,1,0]
	v_cvt_scalef32_pk_f32_fp4 v[14:15], v52, 1.0 op_sel:[1,1,0]
	v_cvt_scalef32_pk_f32_fp4 v[16:17], v53, 1.0
	v_cvt_scalef32_pk_f32_fp4 v[18:19], v53, 1.0 op_sel:[1,0,0]
	v_cvt_scalef32_pk_f32_fp4 v[64:65], v53, 1.0 op_sel:[0,1,0]
	v_cvt_scalef32_pk_f32_fp4 v[66:67], v53, 1.0 op_sel:[1,1,0]
	v_pk_fma_f32 v[24:25], v[8:9], v[190:191], v[24:25] op_sel_hi:[1,0,1]
	v_pk_fma_f32 v[26:27], v[10:11], v[190:191], v[26:27] op_sel_hi:[1,0,1]
	v_pk_fma_f32 v[40:41], v[12:13], v[190:191], v[40:41] op_sel_hi:[1,0,1]
	v_pk_fma_f32 v[42:43], v[14:15], v[190:191], v[42:43] op_sel_hi:[1,0,1]
	v_cvt_scalef32_pk_f32_fp4 v[68:69], v54, 1.0
	v_cvt_scalef32_pk_f32_fp4 v[70:71], v54, 1.0 op_sel:[1,0,0]
	v_cvt_scalef32_pk_f32_fp4 v[72:73], v54, 1.0 op_sel:[0,1,0]
	v_cvt_scalef32_pk_f32_fp4 v[74:75], v54, 1.0 op_sel:[1,1,0]
	v_pk_fma_f32 v[36:37], v[16:17], v[190:191], v[36:37] op_sel_hi:[1,0,1]
	v_pk_fma_f32 v[38:39], v[18:19], v[190:191], v[38:39] op_sel_hi:[1,0,1]
	v_pk_fma_f32 v[4:5], v[64:65], v[190:191], v[4:5] op_sel_hi:[1,0,1]
	v_pk_fma_f32 v[6:7], v[66:67], v[190:191], v[6:7] op_sel_hi:[1,0,1]
	v_cvt_scalef32_pk_f32_fp4 v[8:9], v55, 1.0
	v_cvt_scalef32_pk_f32_fp4 v[10:11], v55, 1.0 op_sel:[1,0,0]
	v_cvt_scalef32_pk_f32_fp4 v[12:13], v55, 1.0 op_sel:[0,1,0]
	v_cvt_scalef32_pk_f32_fp4 v[14:15], v55, 1.0 op_sel:[1,1,0]
	v_pk_fma_f32 v[32:33], v[68:69], v[190:191], v[32:33] op_sel_hi:[1,0,1]
	v_pk_fma_f32 v[34:35], v[70:71], v[190:191], v[34:35] op_sel_hi:[1,0,1]
	v_pk_fma_f32 v[28:29], v[72:73], v[190:191], v[28:29] op_sel_hi:[1,0,1]
	v_pk_fma_f32 v[30:31], v[74:75], v[190:191], v[30:31] op_sel_hi:[1,0,1]
	v_pk_fma_f32 v[20:21], v[8:9], v[190:191], v[20:21] op_sel_hi:[1,0,1]
	v_pk_fma_f32 v[22:23], v[10:11], v[190:191], v[22:23] op_sel_hi:[1,0,1]
	v_pk_fma_f32 v[0:1], v[12:13], v[190:191], v[0:1] op_sel_hi:[1,0,1]
	v_pk_fma_f32 v[2:3], v[14:15], v[190:191], v[2:3] op_sel_hi:[1,0,1]
	s_waitcnt vmcnt(12)
	v_cvt_scalef32_pk_f32_fp4 v[8:9], v56, 1.0
	v_cvt_scalef32_pk_f32_fp4 v[10:11], v56, 1.0 op_sel:[1,0,0]
	v_cvt_scalef32_pk_f32_fp4 v[12:13], v56, 1.0 op_sel:[0,1,0]
	v_cvt_scalef32_pk_f32_fp4 v[14:15], v56, 1.0 op_sel:[1,1,0]
	v_cvt_scalef32_pk_f32_fp4 v[16:17], v57, 1.0
	v_cvt_scalef32_pk_f32_fp4 v[18:19], v57, 1.0 op_sel:[1,0,0]
	v_cvt_scalef32_pk_f32_fp4 v[64:65], v57, 1.0 op_sel:[0,1,0]
	v_cvt_scalef32_pk_f32_fp4 v[66:67], v57, 1.0 op_sel:[1,1,0]
	v_pk_fma_f32 v[24:25], v[8:9], v[190:191], v[24:25] op_sel:[0,1,0]
	v_pk_fma_f32 v[26:27], v[10:11], v[190:191], v[26:27] op_sel:[0,1,0]
	v_pk_fma_f32 v[40:41], v[12:13], v[190:191], v[40:41] op_sel:[0,1,0]
	v_pk_fma_f32 v[42:43], v[14:15], v[190:191], v[42:43] op_sel:[0,1,0]
	v_cvt_scalef32_pk_f32_fp4 v[68:69], v58, 1.0
	v_cvt_scalef32_pk_f32_fp4 v[70:71], v58, 1.0 op_sel:[1,0,0]
	v_cvt_scalef32_pk_f32_fp4 v[72:73], v58, 1.0 op_sel:[0,1,0]
	v_cvt_scalef32_pk_f32_fp4 v[74:75], v58, 1.0 op_sel:[1,1,0]
	v_pk_fma_f32 v[36:37], v[16:17], v[190:191], v[36:37] op_sel:[0,1,0]
	v_pk_fma_f32 v[38:39], v[18:19], v[190:191], v[38:39] op_sel:[0,1,0]
	v_pk_fma_f32 v[4:5], v[64:65], v[190:191], v[4:5] op_sel:[0,1,0]
	v_pk_fma_f32 v[6:7], v[66:67], v[190:191], v[6:7] op_sel:[0,1,0]
	v_cvt_scalef32_pk_f32_fp4 v[8:9], v59, 1.0
	v_cvt_scalef32_pk_f32_fp4 v[10:11], v59, 1.0 op_sel:[1,0,0]
	v_cvt_scalef32_pk_f32_fp4 v[12:13], v59, 1.0 op_sel:[0,1,0]
	v_cvt_scalef32_pk_f32_fp4 v[14:15], v59, 1.0 op_sel:[1,1,0]
	v_pk_fma_f32 v[32:33], v[68:69], v[190:191], v[32:33] op_sel:[0,1,0]
	v_pk_fma_f32 v[34:35], v[70:71], v[190:191], v[34:35] op_sel:[0,1,0]
	v_pk_fma_f32 v[28:29], v[72:73], v[190:191], v[28:29] op_sel:[0,1,0]
	v_pk_fma_f32 v[30:31], v[74:75], v[190:191], v[30:31] op_sel:[0,1,0]
	v_pk_fma_f32 v[20:21], v[8:9], v[190:191], v[20:21] op_sel:[0,1,0]
	v_pk_fma_f32 v[22:23], v[10:11], v[190:191], v[22:23] op_sel:[0,1,0]
	v_pk_fma_f32 v[0:1], v[12:13], v[190:191], v[0:1] op_sel:[0,1,0]
	v_pk_fma_f32 v[2:3], v[14:15], v[190:191], v[2:3] op_sel:[0,1,0]
	s_waitcnt vmcnt(11) lgkmcnt(2)
	v_cvt_scalef32_pk_f32_fp4 v[8:9], v60, 1.0
	v_cvt_scalef32_pk_f32_fp4 v[10:11], v60, 1.0 op_sel:[1,0,0]
	v_cvt_scalef32_pk_f32_fp4 v[12:13], v60, 1.0 op_sel:[0,1,0]
	v_cvt_scalef32_pk_f32_fp4 v[14:15], v60, 1.0 op_sel:[1,1,0]
	v_cvt_scalef32_pk_f32_fp4 v[16:17], v61, 1.0
	v_cvt_scalef32_pk_f32_fp4 v[18:19], v61, 1.0 op_sel:[1,0,0]
	v_cvt_scalef32_pk_f32_fp4 v[64:65], v61, 1.0 op_sel:[0,1,0]
	v_cvt_scalef32_pk_f32_fp4 v[66:67], v61, 1.0 op_sel:[1,1,0]
	v_pk_fma_f32 v[24:25], v[8:9], v[192:193], v[24:25] op_sel_hi:[1,0,1]
	v_pk_fma_f32 v[26:27], v[10:11], v[192:193], v[26:27] op_sel_hi:[1,0,1]
	v_pk_fma_f32 v[40:41], v[12:13], v[192:193], v[40:41] op_sel_hi:[1,0,1]
	v_pk_fma_f32 v[42:43], v[14:15], v[192:193], v[42:43] op_sel_hi:[1,0,1]
	v_cvt_scalef32_pk_f32_fp4 v[68:69], v62, 1.0
	v_cvt_scalef32_pk_f32_fp4 v[70:71], v62, 1.0 op_sel:[1,0,0]
	v_cvt_scalef32_pk_f32_fp4 v[72:73], v62, 1.0 op_sel:[0,1,0]
	v_cvt_scalef32_pk_f32_fp4 v[74:75], v62, 1.0 op_sel:[1,1,0]
	v_pk_fma_f32 v[36:37], v[16:17], v[192:193], v[36:37] op_sel_hi:[1,0,1]
	v_pk_fma_f32 v[38:39], v[18:19], v[192:193], v[38:39] op_sel_hi:[1,0,1]
	v_pk_fma_f32 v[4:5], v[64:65], v[192:193], v[4:5] op_sel_hi:[1,0,1]
	v_pk_fma_f32 v[6:7], v[66:67], v[192:193], v[6:7] op_sel_hi:[1,0,1]
	v_cvt_scalef32_pk_f32_fp4 v[8:9], v63, 1.0
	v_cvt_scalef32_pk_f32_fp4 v[10:11], v63, 1.0 op_sel:[1,0,0]
	v_cvt_scalef32_pk_f32_fp4 v[12:13], v63, 1.0 op_sel:[0,1,0]
	v_cvt_scalef32_pk_f32_fp4 v[14:15], v63, 1.0 op_sel:[1,1,0]
	v_pk_fma_f32 v[32:33], v[68:69], v[192:193], v[32:33] op_sel_hi:[1,0,1]
	v_pk_fma_f32 v[34:35], v[70:71], v[192:193], v[34:35] op_sel_hi:[1,0,1]
	v_pk_fma_f32 v[28:29], v[72:73], v[192:193], v[28:29] op_sel_hi:[1,0,1]
	v_pk_fma_f32 v[30:31], v[74:75], v[192:193], v[30:31] op_sel_hi:[1,0,1]
	v_pk_fma_f32 v[20:21], v[8:9], v[192:193], v[20:21] op_sel_hi:[1,0,1]
	v_pk_fma_f32 v[22:23], v[10:11], v[192:193], v[22:23] op_sel_hi:[1,0,1]
	v_pk_fma_f32 v[0:1], v[12:13], v[192:193], v[0:1] op_sel_hi:[1,0,1]
	v_pk_fma_f32 v[2:3], v[14:15], v[192:193], v[2:3] op_sel_hi:[1,0,1]
	s_waitcnt vmcnt(10)
	v_cvt_scalef32_pk_f32_fp4 v[8:9], v76, 1.0
	v_cvt_scalef32_pk_f32_fp4 v[10:11], v76, 1.0 op_sel:[1,0,0]
	v_cvt_scalef32_pk_f32_fp4 v[12:13], v76, 1.0 op_sel:[0,1,0]
	v_cvt_scalef32_pk_f32_fp4 v[14:15], v76, 1.0 op_sel:[1,1,0]
	v_cvt_scalef32_pk_f32_fp4 v[16:17], v77, 1.0
	v_cvt_scalef32_pk_f32_fp4 v[18:19], v77, 1.0 op_sel:[1,0,0]
	v_cvt_scalef32_pk_f32_fp4 v[64:65], v77, 1.0 op_sel:[0,1,0]
	v_cvt_scalef32_pk_f32_fp4 v[66:67], v77, 1.0 op_sel:[1,1,0]
	v_pk_fma_f32 v[24:25], v[8:9], v[192:193], v[24:25] op_sel:[0,1,0]
	v_pk_fma_f32 v[26:27], v[10:11], v[192:193], v[26:27] op_sel:[0,1,0]
	v_pk_fma_f32 v[40:41], v[12:13], v[192:193], v[40:41] op_sel:[0,1,0]
	v_pk_fma_f32 v[42:43], v[14:15], v[192:193], v[42:43] op_sel:[0,1,0]
	v_cvt_scalef32_pk_f32_fp4 v[68:69], v78, 1.0
	v_cvt_scalef32_pk_f32_fp4 v[70:71], v78, 1.0 op_sel:[1,0,0]
	v_cvt_scalef32_pk_f32_fp4 v[72:73], v78, 1.0 op_sel:[0,1,0]
	v_cvt_scalef32_pk_f32_fp4 v[74:75], v78, 1.0 op_sel:[1,1,0]
	v_pk_fma_f32 v[36:37], v[16:17], v[192:193], v[36:37] op_sel:[0,1,0]
	v_pk_fma_f32 v[38:39], v[18:19], v[192:193], v[38:39] op_sel:[0,1,0]
	v_pk_fma_f32 v[4:5], v[64:65], v[192:193], v[4:5] op_sel:[0,1,0]
	v_pk_fma_f32 v[6:7], v[66:67], v[192:193], v[6:7] op_sel:[0,1,0]
	v_cvt_scalef32_pk_f32_fp4 v[8:9], v79, 1.0
	v_cvt_scalef32_pk_f32_fp4 v[10:11], v79, 1.0 op_sel:[1,0,0]
	v_cvt_scalef32_pk_f32_fp4 v[12:13], v79, 1.0 op_sel:[0,1,0]
	v_cvt_scalef32_pk_f32_fp4 v[14:15], v79, 1.0 op_sel:[1,1,0]
	v_pk_fma_f32 v[32:33], v[68:69], v[192:193], v[32:33] op_sel:[0,1,0]
	v_pk_fma_f32 v[34:35], v[70:71], v[192:193], v[34:35] op_sel:[0,1,0]
	v_pk_fma_f32 v[28:29], v[72:73], v[192:193], v[28:29] op_sel:[0,1,0]
	v_pk_fma_f32 v[30:31], v[74:75], v[192:193], v[30:31] op_sel:[0,1,0]
	v_pk_fma_f32 v[20:21], v[8:9], v[192:193], v[20:21] op_sel:[0,1,0]
	v_pk_fma_f32 v[22:23], v[10:11], v[192:193], v[22:23] op_sel:[0,1,0]
	v_pk_fma_f32 v[0:1], v[12:13], v[192:193], v[0:1] op_sel:[0,1,0]
	v_pk_fma_f32 v[2:3], v[14:15], v[192:193], v[2:3] op_sel:[0,1,0]
	s_waitcnt vmcnt(9)
	v_cvt_scalef32_pk_f32_fp4 v[8:9], v80, 1.0
	v_cvt_scalef32_pk_f32_fp4 v[10:11], v80, 1.0 op_sel:[1,0,0]
	v_cvt_scalef32_pk_f32_fp4 v[12:13], v80, 1.0 op_sel:[0,1,0]
	v_cvt_scalef32_pk_f32_fp4 v[14:15], v80, 1.0 op_sel:[1,1,0]
	v_cvt_scalef32_pk_f32_fp4 v[16:17], v81, 1.0
	v_cvt_scalef32_pk_f32_fp4 v[18:19], v81, 1.0 op_sel:[1,0,0]
	v_cvt_scalef32_pk_f32_fp4 v[64:65], v81, 1.0 op_sel:[0,1,0]
	v_cvt_scalef32_pk_f32_fp4 v[66:67], v81, 1.0 op_sel:[1,1,0]
	v_pk_fma_f32 v[24:25], v[8:9], v[194:195], v[24:25] op_sel_hi:[1,0,1]
	v_pk_fma_f32 v[26:27], v[10:11], v[194:195], v[26:27] op_sel_hi:[1,0,1]
	v_pk_fma_f32 v[40:41], v[12:13], v[194:195], v[40:41] op_sel_hi:[1,0,1]
	v_pk_fma_f32 v[42:43], v[14:15], v[194:195], v[42:43] op_sel_hi:[1,0,1]
	v_cvt_scalef32_pk_f32_fp4 v[68:69], v82, 1.0
	v_cvt_scalef32_pk_f32_fp4 v[70:71], v82, 1.0 op_sel:[1,0,0]
	v_cvt_scalef32_pk_f32_fp4 v[72:73], v82, 1.0 op_sel:[0,1,0]
	v_cvt_scalef32_pk_f32_fp4 v[74:75], v82, 1.0 op_sel:[1,1,0]
	v_pk_fma_f32 v[36:37], v[16:17], v[194:195], v[36:37] op_sel_hi:[1,0,1]
	v_pk_fma_f32 v[38:39], v[18:19], v[194:195], v[38:39] op_sel_hi:[1,0,1]
	v_pk_fma_f32 v[4:5], v[64:65], v[194:195], v[4:5] op_sel_hi:[1,0,1]
	v_pk_fma_f32 v[6:7], v[66:67], v[194:195], v[6:7] op_sel_hi:[1,0,1]
	v_cvt_scalef32_pk_f32_fp4 v[8:9], v83, 1.0
	v_cvt_scalef32_pk_f32_fp4 v[10:11], v83, 1.0 op_sel:[1,0,0]
	v_cvt_scalef32_pk_f32_fp4 v[12:13], v83, 1.0 op_sel:[0,1,0]
	v_cvt_scalef32_pk_f32_fp4 v[14:15], v83, 1.0 op_sel:[1,1,0]
	v_pk_fma_f32 v[32:33], v[68:69], v[194:195], v[32:33] op_sel_hi:[1,0,1]
	v_pk_fma_f32 v[34:35], v[70:71], v[194:195], v[34:35] op_sel_hi:[1,0,1]
	v_pk_fma_f32 v[28:29], v[72:73], v[194:195], v[28:29] op_sel_hi:[1,0,1]
	v_pk_fma_f32 v[30:31], v[74:75], v[194:195], v[30:31] op_sel_hi:[1,0,1]
	v_pk_fma_f32 v[20:21], v[8:9], v[194:195], v[20:21] op_sel_hi:[1,0,1]
	v_pk_fma_f32 v[22:23], v[10:11], v[194:195], v[22:23] op_sel_hi:[1,0,1]
	v_pk_fma_f32 v[0:1], v[12:13], v[194:195], v[0:1] op_sel_hi:[1,0,1]
	v_pk_fma_f32 v[2:3], v[14:15], v[194:195], v[2:3] op_sel_hi:[1,0,1]
	s_waitcnt vmcnt(8)
	v_cvt_scalef32_pk_f32_fp4 v[8:9], v84, 1.0
	v_cvt_scalef32_pk_f32_fp4 v[10:11], v84, 1.0 op_sel:[1,0,0]
	v_cvt_scalef32_pk_f32_fp4 v[12:13], v84, 1.0 op_sel:[0,1,0]
	v_cvt_scalef32_pk_f32_fp4 v[14:15], v84, 1.0 op_sel:[1,1,0]
	v_cvt_scalef32_pk_f32_fp4 v[16:17], v85, 1.0
	v_cvt_scalef32_pk_f32_fp4 v[18:19], v85, 1.0 op_sel:[1,0,0]
	v_cvt_scalef32_pk_f32_fp4 v[64:65], v85, 1.0 op_sel:[0,1,0]
	v_cvt_scalef32_pk_f32_fp4 v[66:67], v85, 1.0 op_sel:[1,1,0]
	v_pk_fma_f32 v[24:25], v[8:9], v[194:195], v[24:25] op_sel:[0,1,0]
	v_pk_fma_f32 v[26:27], v[10:11], v[194:195], v[26:27] op_sel:[0,1,0]
	v_pk_fma_f32 v[40:41], v[12:13], v[194:195], v[40:41] op_sel:[0,1,0]
	v_pk_fma_f32 v[42:43], v[14:15], v[194:195], v[42:43] op_sel:[0,1,0]
	v_cvt_scalef32_pk_f32_fp4 v[68:69], v86, 1.0
	v_cvt_scalef32_pk_f32_fp4 v[70:71], v86, 1.0 op_sel:[1,0,0]
	v_cvt_scalef32_pk_f32_fp4 v[72:73], v86, 1.0 op_sel:[0,1,0]
	v_cvt_scalef32_pk_f32_fp4 v[74:75], v86, 1.0 op_sel:[1,1,0]
	v_pk_fma_f32 v[36:37], v[16:17], v[194:195], v[36:37] op_sel:[0,1,0]
	v_pk_fma_f32 v[38:39], v[18:19], v[194:195], v[38:39] op_sel:[0,1,0]
	v_pk_fma_f32 v[4:5], v[64:65], v[194:195], v[4:5] op_sel:[0,1,0]
	v_pk_fma_f32 v[6:7], v[66:67], v[194:195], v[6:7] op_sel:[0,1,0]
	v_cvt_scalef32_pk_f32_fp4 v[8:9], v87, 1.0
	v_cvt_scalef32_pk_f32_fp4 v[10:11], v87, 1.0 op_sel:[1,0,0]
	v_cvt_scalef32_pk_f32_fp4 v[12:13], v87, 1.0 op_sel:[0,1,0]
	v_cvt_scalef32_pk_f32_fp4 v[14:15], v87, 1.0 op_sel:[1,1,0]
	v_pk_fma_f32 v[32:33], v[68:69], v[194:195], v[32:33] op_sel:[0,1,0]
	v_pk_fma_f32 v[34:35], v[70:71], v[194:195], v[34:35] op_sel:[0,1,0]
	v_pk_fma_f32 v[28:29], v[72:73], v[194:195], v[28:29] op_sel:[0,1,0]
	v_pk_fma_f32 v[30:31], v[74:75], v[194:195], v[30:31] op_sel:[0,1,0]
	v_pk_fma_f32 v[20:21], v[8:9], v[194:195], v[20:21] op_sel:[0,1,0]
	v_pk_fma_f32 v[22:23], v[10:11], v[194:195], v[22:23] op_sel:[0,1,0]
	v_pk_fma_f32 v[0:1], v[12:13], v[194:195], v[0:1] op_sel:[0,1,0]
	v_pk_fma_f32 v[2:3], v[14:15], v[194:195], v[2:3] op_sel:[0,1,0]
	s_waitcnt vmcnt(7) lgkmcnt(1)
	v_cvt_scalef32_pk_f32_fp4 v[8:9], v88, 1.0
	v_cvt_scalef32_pk_f32_fp4 v[10:11], v88, 1.0 op_sel:[1,0,0]
	v_cvt_scalef32_pk_f32_fp4 v[12:13], v88, 1.0 op_sel:[0,1,0]
	v_cvt_scalef32_pk_f32_fp4 v[14:15], v88, 1.0 op_sel:[1,1,0]
	v_cvt_scalef32_pk_f32_fp4 v[16:17], v89, 1.0
	v_cvt_scalef32_pk_f32_fp4 v[18:19], v89, 1.0 op_sel:[1,0,0]
	v_cvt_scalef32_pk_f32_fp4 v[64:65], v89, 1.0 op_sel:[0,1,0]
	v_cvt_scalef32_pk_f32_fp4 v[66:67], v89, 1.0 op_sel:[1,1,0]
	v_pk_fma_f32 v[24:25], v[8:9], v[240:241], v[24:25] op_sel_hi:[1,0,1]
	v_pk_fma_f32 v[26:27], v[10:11], v[240:241], v[26:27] op_sel_hi:[1,0,1]
	v_pk_fma_f32 v[40:41], v[12:13], v[240:241], v[40:41] op_sel_hi:[1,0,1]
	v_pk_fma_f32 v[42:43], v[14:15], v[240:241], v[42:43] op_sel_hi:[1,0,1]
	v_cvt_scalef32_pk_f32_fp4 v[68:69], v90, 1.0
	v_cvt_scalef32_pk_f32_fp4 v[70:71], v90, 1.0 op_sel:[1,0,0]
	v_cvt_scalef32_pk_f32_fp4 v[72:73], v90, 1.0 op_sel:[0,1,0]
	v_cvt_scalef32_pk_f32_fp4 v[74:75], v90, 1.0 op_sel:[1,1,0]
	v_pk_fma_f32 v[36:37], v[16:17], v[240:241], v[36:37] op_sel_hi:[1,0,1]
	v_pk_fma_f32 v[38:39], v[18:19], v[240:241], v[38:39] op_sel_hi:[1,0,1]
	v_pk_fma_f32 v[4:5], v[64:65], v[240:241], v[4:5] op_sel_hi:[1,0,1]
	v_pk_fma_f32 v[6:7], v[66:67], v[240:241], v[6:7] op_sel_hi:[1,0,1]
	v_cvt_scalef32_pk_f32_fp4 v[8:9], v91, 1.0
	v_cvt_scalef32_pk_f32_fp4 v[10:11], v91, 1.0 op_sel:[1,0,0]
	v_cvt_scalef32_pk_f32_fp4 v[12:13], v91, 1.0 op_sel:[0,1,0]
	v_cvt_scalef32_pk_f32_fp4 v[14:15], v91, 1.0 op_sel:[1,1,0]
	v_pk_fma_f32 v[32:33], v[68:69], v[240:241], v[32:33] op_sel_hi:[1,0,1]
	v_pk_fma_f32 v[34:35], v[70:71], v[240:241], v[34:35] op_sel_hi:[1,0,1]
	v_pk_fma_f32 v[28:29], v[72:73], v[240:241], v[28:29] op_sel_hi:[1,0,1]
	v_pk_fma_f32 v[30:31], v[74:75], v[240:241], v[30:31] op_sel_hi:[1,0,1]
	v_pk_fma_f32 v[20:21], v[8:9], v[240:241], v[20:21] op_sel_hi:[1,0,1]
	v_pk_fma_f32 v[22:23], v[10:11], v[240:241], v[22:23] op_sel_hi:[1,0,1]
	v_pk_fma_f32 v[0:1], v[12:13], v[240:241], v[0:1] op_sel_hi:[1,0,1]
	v_pk_fma_f32 v[2:3], v[14:15], v[240:241], v[2:3] op_sel_hi:[1,0,1]
	s_waitcnt vmcnt(6)
	v_cvt_scalef32_pk_f32_fp4 v[8:9], v92, 1.0
	v_cvt_scalef32_pk_f32_fp4 v[10:11], v92, 1.0 op_sel:[1,0,0]
	v_cvt_scalef32_pk_f32_fp4 v[12:13], v92, 1.0 op_sel:[0,1,0]
	v_cvt_scalef32_pk_f32_fp4 v[14:15], v92, 1.0 op_sel:[1,1,0]
	v_cvt_scalef32_pk_f32_fp4 v[16:17], v93, 1.0
	v_cvt_scalef32_pk_f32_fp4 v[18:19], v93, 1.0 op_sel:[1,0,0]
	v_cvt_scalef32_pk_f32_fp4 v[64:65], v93, 1.0 op_sel:[0,1,0]
	v_cvt_scalef32_pk_f32_fp4 v[66:67], v93, 1.0 op_sel:[1,1,0]
	v_pk_fma_f32 v[24:25], v[8:9], v[240:241], v[24:25] op_sel:[0,1,0]
	v_pk_fma_f32 v[26:27], v[10:11], v[240:241], v[26:27] op_sel:[0,1,0]
	v_pk_fma_f32 v[40:41], v[12:13], v[240:241], v[40:41] op_sel:[0,1,0]
	v_pk_fma_f32 v[42:43], v[14:15], v[240:241], v[42:43] op_sel:[0,1,0]
	v_cvt_scalef32_pk_f32_fp4 v[68:69], v94, 1.0
	v_cvt_scalef32_pk_f32_fp4 v[70:71], v94, 1.0 op_sel:[1,0,0]
	v_cvt_scalef32_pk_f32_fp4 v[72:73], v94, 1.0 op_sel:[0,1,0]
	v_cvt_scalef32_pk_f32_fp4 v[74:75], v94, 1.0 op_sel:[1,1,0]
	v_pk_fma_f32 v[36:37], v[16:17], v[240:241], v[36:37] op_sel:[0,1,0]
	v_pk_fma_f32 v[38:39], v[18:19], v[240:241], v[38:39] op_sel:[0,1,0]
	v_pk_fma_f32 v[4:5], v[64:65], v[240:241], v[4:5] op_sel:[0,1,0]
	v_pk_fma_f32 v[6:7], v[66:67], v[240:241], v[6:7] op_sel:[0,1,0]
	v_cvt_scalef32_pk_f32_fp4 v[8:9], v95, 1.0
	v_cvt_scalef32_pk_f32_fp4 v[10:11], v95, 1.0 op_sel:[1,0,0]
	v_cvt_scalef32_pk_f32_fp4 v[12:13], v95, 1.0 op_sel:[0,1,0]
	v_cvt_scalef32_pk_f32_fp4 v[14:15], v95, 1.0 op_sel:[1,1,0]
	v_pk_fma_f32 v[32:33], v[68:69], v[240:241], v[32:33] op_sel:[0,1,0]
	v_pk_fma_f32 v[34:35], v[70:71], v[240:241], v[34:35] op_sel:[0,1,0]
	v_pk_fma_f32 v[28:29], v[72:73], v[240:241], v[28:29] op_sel:[0,1,0]
	v_pk_fma_f32 v[30:31], v[74:75], v[240:241], v[30:31] op_sel:[0,1,0]
	v_pk_fma_f32 v[20:21], v[8:9], v[240:241], v[20:21] op_sel:[0,1,0]
	v_pk_fma_f32 v[22:23], v[10:11], v[240:241], v[22:23] op_sel:[0,1,0]
	v_pk_fma_f32 v[0:1], v[12:13], v[240:241], v[0:1] op_sel:[0,1,0]
	v_pk_fma_f32 v[2:3], v[14:15], v[240:241], v[2:3] op_sel:[0,1,0]
	s_waitcnt vmcnt(5)
	v_cvt_scalef32_pk_f32_fp4 v[8:9], v96, 1.0
	v_cvt_scalef32_pk_f32_fp4 v[10:11], v96, 1.0 op_sel:[1,0,0]
	v_cvt_scalef32_pk_f32_fp4 v[12:13], v96, 1.0 op_sel:[0,1,0]
	v_cvt_scalef32_pk_f32_fp4 v[14:15], v96, 1.0 op_sel:[1,1,0]
	v_cvt_scalef32_pk_f32_fp4 v[16:17], v97, 1.0
	v_cvt_scalef32_pk_f32_fp4 v[18:19], v97, 1.0 op_sel:[1,0,0]
	v_cvt_scalef32_pk_f32_fp4 v[64:65], v97, 1.0 op_sel:[0,1,0]
	v_cvt_scalef32_pk_f32_fp4 v[66:67], v97, 1.0 op_sel:[1,1,0]
	v_pk_fma_f32 v[24:25], v[8:9], v[242:243], v[24:25] op_sel_hi:[1,0,1]
	v_pk_fma_f32 v[26:27], v[10:11], v[242:243], v[26:27] op_sel_hi:[1,0,1]
	v_pk_fma_f32 v[40:41], v[12:13], v[242:243], v[40:41] op_sel_hi:[1,0,1]
	v_pk_fma_f32 v[42:43], v[14:15], v[242:243], v[42:43] op_sel_hi:[1,0,1]
	v_cvt_scalef32_pk_f32_fp4 v[68:69], v98, 1.0
	v_cvt_scalef32_pk_f32_fp4 v[70:71], v98, 1.0 op_sel:[1,0,0]
	v_cvt_scalef32_pk_f32_fp4 v[72:73], v98, 1.0 op_sel:[0,1,0]
	v_cvt_scalef32_pk_f32_fp4 v[74:75], v98, 1.0 op_sel:[1,1,0]
	v_pk_fma_f32 v[36:37], v[16:17], v[242:243], v[36:37] op_sel_hi:[1,0,1]
	v_pk_fma_f32 v[38:39], v[18:19], v[242:243], v[38:39] op_sel_hi:[1,0,1]
	v_pk_fma_f32 v[4:5], v[64:65], v[242:243], v[4:5] op_sel_hi:[1,0,1]
	v_pk_fma_f32 v[6:7], v[66:67], v[242:243], v[6:7] op_sel_hi:[1,0,1]
	v_cvt_scalef32_pk_f32_fp4 v[8:9], v99, 1.0
	v_cvt_scalef32_pk_f32_fp4 v[10:11], v99, 1.0 op_sel:[1,0,0]
	v_cvt_scalef32_pk_f32_fp4 v[12:13], v99, 1.0 op_sel:[0,1,0]
	v_cvt_scalef32_pk_f32_fp4 v[14:15], v99, 1.0 op_sel:[1,1,0]
	v_pk_fma_f32 v[32:33], v[68:69], v[242:243], v[32:33] op_sel_hi:[1,0,1]
	v_pk_fma_f32 v[34:35], v[70:71], v[242:243], v[34:35] op_sel_hi:[1,0,1]
	v_pk_fma_f32 v[28:29], v[72:73], v[242:243], v[28:29] op_sel_hi:[1,0,1]
	v_pk_fma_f32 v[30:31], v[74:75], v[242:243], v[30:31] op_sel_hi:[1,0,1]
	v_pk_fma_f32 v[20:21], v[8:9], v[242:243], v[20:21] op_sel_hi:[1,0,1]
	v_pk_fma_f32 v[22:23], v[10:11], v[242:243], v[22:23] op_sel_hi:[1,0,1]
	v_pk_fma_f32 v[0:1], v[12:13], v[242:243], v[0:1] op_sel_hi:[1,0,1]
	v_pk_fma_f32 v[2:3], v[14:15], v[242:243], v[2:3] op_sel_hi:[1,0,1]
	s_waitcnt vmcnt(4)
	v_cvt_scalef32_pk_f32_fp4 v[8:9], v100, 1.0
	v_cvt_scalef32_pk_f32_fp4 v[10:11], v100, 1.0 op_sel:[1,0,0]
	v_cvt_scalef32_pk_f32_fp4 v[12:13], v100, 1.0 op_sel:[0,1,0]
	v_cvt_scalef32_pk_f32_fp4 v[14:15], v100, 1.0 op_sel:[1,1,0]
	v_cvt_scalef32_pk_f32_fp4 v[16:17], v101, 1.0
	v_cvt_scalef32_pk_f32_fp4 v[18:19], v101, 1.0 op_sel:[1,0,0]
	v_cvt_scalef32_pk_f32_fp4 v[64:65], v101, 1.0 op_sel:[0,1,0]
	v_cvt_scalef32_pk_f32_fp4 v[66:67], v101, 1.0 op_sel:[1,1,0]
	v_pk_fma_f32 v[24:25], v[8:9], v[242:243], v[24:25] op_sel:[0,1,0]
	v_pk_fma_f32 v[26:27], v[10:11], v[242:243], v[26:27] op_sel:[0,1,0]
	v_pk_fma_f32 v[40:41], v[12:13], v[242:243], v[40:41] op_sel:[0,1,0]
	v_pk_fma_f32 v[42:43], v[14:15], v[242:243], v[42:43] op_sel:[0,1,0]
	v_cvt_scalef32_pk_f32_fp4 v[68:69], v102, 1.0
	v_cvt_scalef32_pk_f32_fp4 v[70:71], v102, 1.0 op_sel:[1,0,0]
	v_cvt_scalef32_pk_f32_fp4 v[72:73], v102, 1.0 op_sel:[0,1,0]
	v_cvt_scalef32_pk_f32_fp4 v[74:75], v102, 1.0 op_sel:[1,1,0]
	v_pk_fma_f32 v[36:37], v[16:17], v[242:243], v[36:37] op_sel:[0,1,0]
	v_pk_fma_f32 v[38:39], v[18:19], v[242:243], v[38:39] op_sel:[0,1,0]
	v_pk_fma_f32 v[4:5], v[64:65], v[242:243], v[4:5] op_sel:[0,1,0]
	v_pk_fma_f32 v[6:7], v[66:67], v[242:243], v[6:7] op_sel:[0,1,0]
	v_cvt_scalef32_pk_f32_fp4 v[8:9], v103, 1.0
	v_cvt_scalef32_pk_f32_fp4 v[10:11], v103, 1.0 op_sel:[1,0,0]
	v_cvt_scalef32_pk_f32_fp4 v[12:13], v103, 1.0 op_sel:[0,1,0]
	v_cvt_scalef32_pk_f32_fp4 v[14:15], v103, 1.0 op_sel:[1,1,0]
	v_pk_fma_f32 v[32:33], v[68:69], v[242:243], v[32:33] op_sel:[0,1,0]
	v_pk_fma_f32 v[34:35], v[70:71], v[242:243], v[34:35] op_sel:[0,1,0]
	v_pk_fma_f32 v[28:29], v[72:73], v[242:243], v[28:29] op_sel:[0,1,0]
	v_pk_fma_f32 v[30:31], v[74:75], v[242:243], v[30:31] op_sel:[0,1,0]
	v_pk_fma_f32 v[20:21], v[8:9], v[242:243], v[20:21] op_sel:[0,1,0]
	v_pk_fma_f32 v[22:23], v[10:11], v[242:243], v[22:23] op_sel:[0,1,0]
	v_pk_fma_f32 v[0:1], v[12:13], v[242:243], v[0:1] op_sel:[0,1,0]
	v_pk_fma_f32 v[2:3], v[14:15], v[242:243], v[2:3] op_sel:[0,1,0]
	s_waitcnt vmcnt(3) lgkmcnt(0)
	v_cvt_scalef32_pk_f32_fp4 v[8:9], v172, 1.0
	v_cvt_scalef32_pk_f32_fp4 v[10:11], v172, 1.0 op_sel:[1,0,0]
	v_cvt_scalef32_pk_f32_fp4 v[12:13], v172, 1.0 op_sel:[0,1,0]
	v_cvt_scalef32_pk_f32_fp4 v[14:15], v172, 1.0 op_sel:[1,1,0]
	v_cvt_scalef32_pk_f32_fp4 v[16:17], v173, 1.0
	v_cvt_scalef32_pk_f32_fp4 v[18:19], v173, 1.0 op_sel:[1,0,0]
	v_cvt_scalef32_pk_f32_fp4 v[64:65], v173, 1.0 op_sel:[0,1,0]
	v_cvt_scalef32_pk_f32_fp4 v[66:67], v173, 1.0 op_sel:[1,1,0]
	v_pk_fma_f32 v[24:25], v[8:9], v[244:245], v[24:25] op_sel_hi:[1,0,1]
	v_pk_fma_f32 v[26:27], v[10:11], v[244:245], v[26:27] op_sel_hi:[1,0,1]
	v_pk_fma_f32 v[40:41], v[12:13], v[244:245], v[40:41] op_sel_hi:[1,0,1]
	v_pk_fma_f32 v[42:43], v[14:15], v[244:245], v[42:43] op_sel_hi:[1,0,1]
	v_cvt_scalef32_pk_f32_fp4 v[68:69], v174, 1.0
	v_cvt_scalef32_pk_f32_fp4 v[70:71], v174, 1.0 op_sel:[1,0,0]
	v_cvt_scalef32_pk_f32_fp4 v[72:73], v174, 1.0 op_sel:[0,1,0]
	v_cvt_scalef32_pk_f32_fp4 v[74:75], v174, 1.0 op_sel:[1,1,0]
	v_pk_fma_f32 v[36:37], v[16:17], v[244:245], v[36:37] op_sel_hi:[1,0,1]
	v_pk_fma_f32 v[38:39], v[18:19], v[244:245], v[38:39] op_sel_hi:[1,0,1]
	v_pk_fma_f32 v[4:5], v[64:65], v[244:245], v[4:5] op_sel_hi:[1,0,1]
	v_pk_fma_f32 v[6:7], v[66:67], v[244:245], v[6:7] op_sel_hi:[1,0,1]
	v_cvt_scalef32_pk_f32_fp4 v[8:9], v175, 1.0
	v_cvt_scalef32_pk_f32_fp4 v[10:11], v175, 1.0 op_sel:[1,0,0]
	v_cvt_scalef32_pk_f32_fp4 v[12:13], v175, 1.0 op_sel:[0,1,0]
	v_cvt_scalef32_pk_f32_fp4 v[14:15], v175, 1.0 op_sel:[1,1,0]
	v_pk_fma_f32 v[32:33], v[68:69], v[244:245], v[32:33] op_sel_hi:[1,0,1]
	v_pk_fma_f32 v[34:35], v[70:71], v[244:245], v[34:35] op_sel_hi:[1,0,1]
	v_pk_fma_f32 v[28:29], v[72:73], v[244:245], v[28:29] op_sel_hi:[1,0,1]
	v_pk_fma_f32 v[30:31], v[74:75], v[244:245], v[30:31] op_sel_hi:[1,0,1]
	v_pk_fma_f32 v[20:21], v[8:9], v[244:245], v[20:21] op_sel_hi:[1,0,1]
	v_pk_fma_f32 v[22:23], v[10:11], v[244:245], v[22:23] op_sel_hi:[1,0,1]
	v_pk_fma_f32 v[0:1], v[12:13], v[244:245], v[0:1] op_sel_hi:[1,0,1]
	v_pk_fma_f32 v[2:3], v[14:15], v[244:245], v[2:3] op_sel_hi:[1,0,1]
	s_waitcnt vmcnt(2)
	v_cvt_scalef32_pk_f32_fp4 v[8:9], v176, 1.0
	v_cvt_scalef32_pk_f32_fp4 v[10:11], v176, 1.0 op_sel:[1,0,0]
	v_cvt_scalef32_pk_f32_fp4 v[12:13], v176, 1.0 op_sel:[0,1,0]
	v_cvt_scalef32_pk_f32_fp4 v[14:15], v176, 1.0 op_sel:[1,1,0]
	v_cvt_scalef32_pk_f32_fp4 v[16:17], v177, 1.0
	v_cvt_scalef32_pk_f32_fp4 v[18:19], v177, 1.0 op_sel:[1,0,0]
	v_cvt_scalef32_pk_f32_fp4 v[64:65], v177, 1.0 op_sel:[0,1,0]
	v_cvt_scalef32_pk_f32_fp4 v[66:67], v177, 1.0 op_sel:[1,1,0]
	v_pk_fma_f32 v[24:25], v[8:9], v[244:245], v[24:25] op_sel:[0,1,0]
	v_pk_fma_f32 v[26:27], v[10:11], v[244:245], v[26:27] op_sel:[0,1,0]
	v_pk_fma_f32 v[40:41], v[12:13], v[244:245], v[40:41] op_sel:[0,1,0]
	v_pk_fma_f32 v[42:43], v[14:15], v[244:245], v[42:43] op_sel:[0,1,0]
	v_cvt_scalef32_pk_f32_fp4 v[68:69], v178, 1.0
	v_cvt_scalef32_pk_f32_fp4 v[70:71], v178, 1.0 op_sel:[1,0,0]
	v_cvt_scalef32_pk_f32_fp4 v[72:73], v178, 1.0 op_sel:[0,1,0]
	v_cvt_scalef32_pk_f32_fp4 v[74:75], v178, 1.0 op_sel:[1,1,0]
	v_pk_fma_f32 v[36:37], v[16:17], v[244:245], v[36:37] op_sel:[0,1,0]
	v_pk_fma_f32 v[38:39], v[18:19], v[244:245], v[38:39] op_sel:[0,1,0]
	v_pk_fma_f32 v[4:5], v[64:65], v[244:245], v[4:5] op_sel:[0,1,0]
	v_pk_fma_f32 v[6:7], v[66:67], v[244:245], v[6:7] op_sel:[0,1,0]
	v_cvt_scalef32_pk_f32_fp4 v[8:9], v179, 1.0
	v_cvt_scalef32_pk_f32_fp4 v[10:11], v179, 1.0 op_sel:[1,0,0]
	v_cvt_scalef32_pk_f32_fp4 v[12:13], v179, 1.0 op_sel:[0,1,0]
	v_cvt_scalef32_pk_f32_fp4 v[14:15], v179, 1.0 op_sel:[1,1,0]
	v_pk_fma_f32 v[32:33], v[68:69], v[244:245], v[32:33] op_sel:[0,1,0]
	v_pk_fma_f32 v[34:35], v[70:71], v[244:245], v[34:35] op_sel:[0,1,0]
	v_pk_fma_f32 v[28:29], v[72:73], v[244:245], v[28:29] op_sel:[0,1,0]
	v_pk_fma_f32 v[30:31], v[74:75], v[244:245], v[30:31] op_sel:[0,1,0]
	v_pk_fma_f32 v[20:21], v[8:9], v[244:245], v[20:21] op_sel:[0,1,0]
	v_pk_fma_f32 v[22:23], v[10:11], v[244:245], v[22:23] op_sel:[0,1,0]
	v_pk_fma_f32 v[0:1], v[12:13], v[244:245], v[0:1] op_sel:[0,1,0]
	v_pk_fma_f32 v[2:3], v[14:15], v[244:245], v[2:3] op_sel:[0,1,0]
	s_waitcnt vmcnt(1)
	v_cvt_scalef32_pk_f32_fp4 v[8:9], v180, 1.0
	v_cvt_scalef32_pk_f32_fp4 v[10:11], v180, 1.0 op_sel:[1,0,0]
	v_cvt_scalef32_pk_f32_fp4 v[12:13], v180, 1.0 op_sel:[0,1,0]
	v_cvt_scalef32_pk_f32_fp4 v[14:15], v180, 1.0 op_sel:[1,1,0]
	v_cvt_scalef32_pk_f32_fp4 v[16:17], v181, 1.0
	v_cvt_scalef32_pk_f32_fp4 v[18:19], v181, 1.0 op_sel:[1,0,0]
	v_cvt_scalef32_pk_f32_fp4 v[64:65], v181, 1.0 op_sel:[0,1,0]
	v_cvt_scalef32_pk_f32_fp4 v[66:67], v181, 1.0 op_sel:[1,1,0]
	v_pk_fma_f32 v[24:25], v[8:9], v[246:247], v[24:25] op_sel_hi:[1,0,1]
	v_pk_fma_f32 v[26:27], v[10:11], v[246:247], v[26:27] op_sel_hi:[1,0,1]
	v_pk_fma_f32 v[40:41], v[12:13], v[246:247], v[40:41] op_sel_hi:[1,0,1]
	v_pk_fma_f32 v[42:43], v[14:15], v[246:247], v[42:43] op_sel_hi:[1,0,1]
	v_cvt_scalef32_pk_f32_fp4 v[68:69], v182, 1.0
	v_cvt_scalef32_pk_f32_fp4 v[70:71], v182, 1.0 op_sel:[1,0,0]
	v_cvt_scalef32_pk_f32_fp4 v[72:73], v182, 1.0 op_sel:[0,1,0]
	v_cvt_scalef32_pk_f32_fp4 v[74:75], v182, 1.0 op_sel:[1,1,0]
	v_pk_fma_f32 v[36:37], v[16:17], v[246:247], v[36:37] op_sel_hi:[1,0,1]
	v_pk_fma_f32 v[38:39], v[18:19], v[246:247], v[38:39] op_sel_hi:[1,0,1]
	v_pk_fma_f32 v[4:5], v[64:65], v[246:247], v[4:5] op_sel_hi:[1,0,1]
	v_pk_fma_f32 v[6:7], v[66:67], v[246:247], v[6:7] op_sel_hi:[1,0,1]
	v_cvt_scalef32_pk_f32_fp4 v[8:9], v183, 1.0
	v_cvt_scalef32_pk_f32_fp4 v[10:11], v183, 1.0 op_sel:[1,0,0]
	v_cvt_scalef32_pk_f32_fp4 v[12:13], v183, 1.0 op_sel:[0,1,0]
	v_cvt_scalef32_pk_f32_fp4 v[14:15], v183, 1.0 op_sel:[1,1,0]
	v_pk_fma_f32 v[32:33], v[68:69], v[246:247], v[32:33] op_sel_hi:[1,0,1]
	v_pk_fma_f32 v[34:35], v[70:71], v[246:247], v[34:35] op_sel_hi:[1,0,1]
	v_pk_fma_f32 v[28:29], v[72:73], v[246:247], v[28:29] op_sel_hi:[1,0,1]
	v_pk_fma_f32 v[30:31], v[74:75], v[246:247], v[30:31] op_sel_hi:[1,0,1]
	v_pk_fma_f32 v[20:21], v[8:9], v[246:247], v[20:21] op_sel_hi:[1,0,1]
	v_pk_fma_f32 v[22:23], v[10:11], v[246:247], v[22:23] op_sel_hi:[1,0,1]
	v_pk_fma_f32 v[0:1], v[12:13], v[246:247], v[0:1] op_sel_hi:[1,0,1]
	v_pk_fma_f32 v[2:3], v[14:15], v[246:247], v[2:3] op_sel_hi:[1,0,1]
	s_waitcnt vmcnt(0)
	v_cvt_scalef32_pk_f32_fp4 v[8:9], v184, 1.0
	v_cvt_scalef32_pk_f32_fp4 v[10:11], v184, 1.0 op_sel:[1,0,0]
	v_cvt_scalef32_pk_f32_fp4 v[12:13], v184, 1.0 op_sel:[0,1,0]
	v_cvt_scalef32_pk_f32_fp4 v[14:15], v184, 1.0 op_sel:[1,1,0]
	v_cvt_scalef32_pk_f32_fp4 v[16:17], v185, 1.0
	v_cvt_scalef32_pk_f32_fp4 v[18:19], v185, 1.0 op_sel:[1,0,0]
	v_cvt_scalef32_pk_f32_fp4 v[64:65], v185, 1.0 op_sel:[0,1,0]
	v_cvt_scalef32_pk_f32_fp4 v[66:67], v185, 1.0 op_sel:[1,1,0]
	v_pk_fma_f32 v[24:25], v[8:9], v[246:247], v[24:25] op_sel:[0,1,0]
	v_pk_fma_f32 v[26:27], v[10:11], v[246:247], v[26:27] op_sel:[0,1,0]
	v_pk_fma_f32 v[40:41], v[12:13], v[246:247], v[40:41] op_sel:[0,1,0]
	v_pk_fma_f32 v[42:43], v[14:15], v[246:247], v[42:43] op_sel:[0,1,0]
	v_cvt_scalef32_pk_f32_fp4 v[68:69], v186, 1.0
	v_cvt_scalef32_pk_f32_fp4 v[70:71], v186, 1.0 op_sel:[1,0,0]
	v_cvt_scalef32_pk_f32_fp4 v[72:73], v186, 1.0 op_sel:[0,1,0]
	v_cvt_scalef32_pk_f32_fp4 v[74:75], v186, 1.0 op_sel:[1,1,0]
	v_pk_fma_f32 v[36:37], v[16:17], v[246:247], v[36:37] op_sel:[0,1,0]
	v_pk_fma_f32 v[38:39], v[18:19], v[246:247], v[38:39] op_sel:[0,1,0]
	v_pk_fma_f32 v[4:5], v[64:65], v[246:247], v[4:5] op_sel:[0,1,0]
	v_pk_fma_f32 v[6:7], v[66:67], v[246:247], v[6:7] op_sel:[0,1,0]
	v_cvt_scalef32_pk_f32_fp4 v[8:9], v187, 1.0
	v_cvt_scalef32_pk_f32_fp4 v[10:11], v187, 1.0 op_sel:[1,0,0]
	v_cvt_scalef32_pk_f32_fp4 v[12:13], v187, 1.0 op_sel:[0,1,0]
	v_cvt_scalef32_pk_f32_fp4 v[14:15], v187, 1.0 op_sel:[1,1,0]
	v_pk_fma_f32 v[32:33], v[68:69], v[246:247], v[32:33] op_sel:[0,1,0]
	v_pk_fma_f32 v[34:35], v[70:71], v[246:247], v[34:35] op_sel:[0,1,0]
	v_pk_fma_f32 v[28:29], v[72:73], v[246:247], v[28:29] op_sel:[0,1,0]
	v_pk_fma_f32 v[30:31], v[74:75], v[246:247], v[30:31] op_sel:[0,1,0]
	v_pk_fma_f32 v[20:21], v[8:9], v[246:247], v[20:21] op_sel:[0,1,0]
	v_pk_fma_f32 v[22:23], v[10:11], v[246:247], v[22:23] op_sel:[0,1,0]
	v_pk_fma_f32 v[0:1], v[12:13], v[246:247], v[0:1] op_sel:[0,1,0]
	v_pk_fma_f32 v[2:3], v[14:15], v[246:247], v[2:3] op_sel:[0,1,0]
	s_waitcnt lgkmcnt(0)
	ds_write_b128 v166, v[24:27]
	ds_write_b128 v166, v[40:43] offset:16
	ds_write_b128 v166, v[36:39] offset:32
	ds_write_b128 v166, v[4:7] offset:48
	ds_write_b128 v166, v[32:35] offset:64
	ds_write_b128 v166, v[28:31] offset:80
	ds_write_b128 v166, v[20:23] offset:96
	ds_write_b128 v166, v[0:3] offset:112
	v_add_u32_e32 v1, 0xffffc000, v152
	v_lshrrev_b32_e32 v1, 3, v1
	v_ashrrev_i32_e32 v0, 11, v152
	v_add_u32_e32 v1, 8, v1
	v_cmp_gt_i32_e32 vcc, s61, v152
	v_ashrrev_i32_e32 v153, 31, v152
	s_waitcnt lgkmcnt(0)
	v_mov_b32_e32 v137, v107
	v_cndmask_b32_e32 v2, v1, v0, vcc
	v_mov_b64_e32 v[0:1], s[92:93]
	v_mad_i64_i32 v[0:1], s[44:45], v2, s62, v[0:1]
	v_lshlrev_b64 v[2:3], 12, v[152:153]
	v_lshl_add_u64 v[12:13], v[126:127], 0, v[2:3]
	v_lshl_add_u64 v[16:17], v[0:1], 0, s[40:41]
	v_lshlrev_b64 v[4:5], 13, v[152:153]
	v_lshl_add_u64 v[18:19], s[90:91], 0, v[4:5]
	v_mov_b32_e32 v139, v107
	v_mov_b32_e32 v141, v107
	v_mov_b32_e32 v143, v107
	v_mov_b32_e32 v145, v107
	v_mov_b32_e32 v147, v107
	v_mov_b32_e32 v149, v107
	v_mov_b32_e32 v151, v107
	global_load_dwordx2 v[44:45], v[12:13], off
	v_lshl_add_u64 v[0:1], v[16:17], 0, v[136:137]
	global_load_dwordx4 v[60:63], v[0:1], off
	global_load_dwordx2 v[46:47], v[12:13], off offset:512
	v_lshl_add_u64 v[0:1], v[16:17], 0, v[138:139]
	global_load_dwordx4 v[76:79], v[0:1], off
	global_load_dwordx2 v[48:49], v[12:13], off offset:1024
	v_lshl_add_u64 v[0:1], v[16:17], 0, v[140:141]
	global_load_dwordx4 v[80:83], v[0:1], off
	global_load_dwordx2 v[50:51], v[12:13], off offset:1536
	v_lshl_add_u64 v[0:1], v[16:17], 0, v[142:143]
	global_load_dwordx4 v[84:87], v[0:1], off
	global_load_dwordx2 v[52:53], v[12:13], off offset:2048
	v_lshl_add_u64 v[0:1], v[16:17], 0, v[144:145]
	global_load_dwordx4 v[88:91], v[0:1], off
	global_load_dwordx2 v[54:55], v[12:13], off offset:2560
	v_lshl_add_u64 v[0:1], v[16:17], 0, v[146:147]
	global_load_dwordx4 v[92:95], v[0:1], off
	global_load_dwordx2 v[56:57], v[12:13], off offset:3072
	v_lshl_add_u64 v[0:1], v[16:17], 0, v[148:149]
	global_load_dwordx4 v[96:99], v[0:1], off
	global_load_dwordx2 v[58:59], v[12:13], off offset:3584
	v_lshl_add_u64 v[0:1], v[16:17], 0, v[150:151]
	global_load_dwordx4 v[100:103], v[0:1], off
	ds_read_b128 v[172:175], v167
	ds_read_b128 v[176:179], v167 offset:1152
	ds_read_b128 v[180:183], v167 offset:2304
	ds_read_b128 v[184:187], v167 offset:3456
	ds_read_b128 v[188:191], v167 offset:4608
	ds_read_b128 v[192:195], v167 offset:5760
	ds_read_b128 v[240:243], v167 offset:6912
	ds_read_b128 v[244:247], v167 offset:8064
	v_lshl_add_u64 v[20:21], v[18:19], 0, v[136:137]
	v_lshl_add_u64 v[22:23], v[18:19], 0, v[144:145]
	s_waitcnt vmcnt(14) lgkmcnt(7)
	v_lshlrev_b32_e32 v0, 16, v44
	v_and_b32_e32 v1, 0xffff0000, v44
	v_lshlrev_b32_e32 v2, 16, v45
	v_and_b32_e32 v3, 0xffff0000, v45
	v_pk_fma_f32 v[60:61], v[172:173], v[60:61], v[0:1]
	v_pk_fma_f32 v[62:63], v[174:175], v[62:63], v[2:3]
	global_store_dwordx4 v[20:21], v[60:63], off
	s_waitcnt vmcnt(13) lgkmcnt(6)
	v_lshlrev_b32_e32 v0, 16, v46
	v_and_b32_e32 v1, 0xffff0000, v46
	v_lshlrev_b32_e32 v2, 16, v47
	v_and_b32_e32 v3, 0xffff0000, v47
	v_pk_fma_f32 v[76:77], v[176:177], v[76:77], v[0:1]
	v_pk_fma_f32 v[78:79], v[178:179], v[78:79], v[2:3]
	global_store_dwordx4 v[20:21], v[76:79], off offset:1024
	s_waitcnt vmcnt(12) lgkmcnt(5)
	v_lshlrev_b32_e32 v0, 16, v48
	v_and_b32_e32 v1, 0xffff0000, v48
	v_lshlrev_b32_e32 v2, 16, v49
	v_and_b32_e32 v3, 0xffff0000, v49
	v_pk_fma_f32 v[80:81], v[180:181], v[80:81], v[0:1]
	v_pk_fma_f32 v[82:83], v[182:183], v[82:83], v[2:3]
	global_store_dwordx4 v[20:21], v[80:83], off offset:2048
	s_waitcnt vmcnt(11) lgkmcnt(4)
	v_lshlrev_b32_e32 v0, 16, v50
	v_and_b32_e32 v1, 0xffff0000, v50
	v_lshlrev_b32_e32 v2, 16, v51
	v_and_b32_e32 v3, 0xffff0000, v51
	v_pk_fma_f32 v[84:85], v[184:185], v[84:85], v[0:1]
	v_pk_fma_f32 v[86:87], v[186:187], v[86:87], v[2:3]
	global_store_dwordx4 v[20:21], v[84:87], off offset:3072
	s_waitcnt vmcnt(10) lgkmcnt(3)
	v_lshlrev_b32_e32 v0, 16, v52
	v_and_b32_e32 v1, 0xffff0000, v52
	v_lshlrev_b32_e32 v2, 16, v53
	v_and_b32_e32 v3, 0xffff0000, v53
	v_pk_fma_f32 v[88:89], v[188:189], v[88:89], v[0:1]
	v_pk_fma_f32 v[90:91], v[190:191], v[90:91], v[2:3]
	global_store_dwordx4 v[22:23], v[88:91], off
	s_waitcnt vmcnt(9) lgkmcnt(2)
	v_lshlrev_b32_e32 v0, 16, v54
	v_and_b32_e32 v1, 0xffff0000, v54
	v_lshlrev_b32_e32 v2, 16, v55
	v_and_b32_e32 v3, 0xffff0000, v55
	v_pk_fma_f32 v[92:93], v[192:193], v[92:93], v[0:1]
	v_pk_fma_f32 v[94:95], v[194:195], v[94:95], v[2:3]
	global_store_dwordx4 v[22:23], v[92:95], off offset:1024
	s_waitcnt vmcnt(8) lgkmcnt(1)
	v_lshlrev_b32_e32 v0, 16, v56
	v_and_b32_e32 v1, 0xffff0000, v56
	v_lshlrev_b32_e32 v2, 16, v57
	v_and_b32_e32 v3, 0xffff0000, v57
	v_pk_fma_f32 v[96:97], v[240:241], v[96:97], v[0:1]
	v_pk_fma_f32 v[98:99], v[242:243], v[98:99], v[2:3]
	global_store_dwordx4 v[22:23], v[96:99], off offset:2048
	s_waitcnt vmcnt(7) lgkmcnt(0)
	v_lshlrev_b32_e32 v0, 16, v58
	v_and_b32_e32 v1, 0xffff0000, v58
	v_lshlrev_b32_e32 v2, 16, v59
	v_and_b32_e32 v3, 0xffff0000, v59
	v_pk_fma_f32 v[100:101], v[244:245], v[100:101], v[0:1]
	v_pk_fma_f32 v[102:103], v[246:247], v[102:103], v[2:3]
	global_store_dwordx4 v[22:23], v[100:103], off offset:3072
	s_waitcnt lgkmcnt(0)
	s_branch .LBB0_2054
